# in-proj rope epilogue: in-place two-element half-wave swap (both outputs of a rope pair formed in one lane), exchange copies / selects / sine sign selects removed (-433 instructions per rope unit and
# speedup vs baseline: 1.0016x; 1.0016x over previous
; __device__ __forceinline__ unsigned cvt_pk_bf16(float lo, float hi) { unsigned r; asm volatile("v_cvt_pk_bf16_f32 %0, %1, %2" : "=v"(r) : "v"(lo), "v"(hi)); return r; }
;     __device__ __forceinline__ void operator()(const f32x4 (&acc)[2][2][4][2], const Unit& u, int wr, int wc, int fr, int fq) const {
;     ...
;                 for (int m = 0; m < 4; ++m) {
;                     const int row = u.pm * BM + ai * HALF + wr * 64 + m * 16 + fr;
;                     const bool lat = row < MLAT; const int t = row & (SEQ - 1); const int pos = axis ? (t & 63) : (t >> 6);
;                     f32x4 c0 = *(const f32x4*)(ropec + pos * 16 + pb), c1 = *(const f32x4*)(ropec + pos * 16 + pb + 4), s0 = *(const f32x4*)(ropes + pos * 16 + pb), s1 = *(const f32x4*)(ropes + pos * 16 + pb + 4);
;                     if (!lat) { c0 = (f32x4){1.f, 1.f, 1.f, 1.f}; c1 = c0; s0 = (f32x4){0.f, 0.f, 0.f, 0.f}; s1 = s0; }
;                     if (!upper) { s0 = -s0; s1 = -s1; }
;                     bf16_t* rowp = dst + (size_t)row * DQK + u.pn * BM + wc * 32 + 8 * fq;
; #pragma unroll
;                     for (int bj = 0; bj < 2; ++bj) { const f32x4 a0 = acc[ai][bj][m][0], a1 = acc[ai][bj][m][1]; f32x4 p0, p1;
; #pragma unroll
;                         for (int i = 0; i < 4; ++i) {
;                             auto r0 = __builtin_amdgcn_permlane32_swap(__float_as_uint(a0[i]), __float_as_uint(a0[i]), false, false); p0[i] = __uint_as_float(upper ? r0[0] : r0[1]);
;                             auto r1 = __builtin_amdgcn_permlane32_swap(__float_as_uint(a1[i]), __float_as_uint(a1[i]), false, false); p1[i] = __uint_as_float(upper ? r1[0] : r1[1]); }
;                         const f32x4 o0 = (a0 * c0 + p0 * s0) * sc, o1 = (a1 * c1 + p1 * s1) * sc;
;                         { float ss = ((o0[0] * o0[0] + o0[1] * o0[1]) + (o0[2] * o0[2] + o0[3] * o0[3])) + ((o1[0] * o1[0] + o1[1] * o1[1]) + (o1[2] * o1[2] + o1[3] * o1[3]));
;                           ss += __shfl_xor(ss, 16); ss += __shfl_xor(ss, 32); gmax = fmaxf(gmax, ss); }
;                         u32x4 w; w.x = cvt_pk_bf16(o0[0], o0[1]); w.y = cvt_pk_bf16(o0[2], o0[3]); w.z = cvt_pk_bf16(o1[0], o1[1]); w.w = cvt_pk_bf16(o1[2], o1[3]);
;                         *(u32x4*)(rowp + bj * HALF) = w; }
.LBB0_676:
	s_or_b64 exec, exec, s[2:3]
	s_waitcnt vmcnt(0)
	v_cndmask_b32_e64 v230, v138, v139, s[0:1]
	v_cndmask_b32_e64 v238, v138, v139, s[0:1]
	v_cndmask_b32_e64 v226, v140, v141, s[0:1]
	v_cndmask_b32_e64 v234, v140, v141, s[0:1]
	v_and_b32_e32 v179, 64, v167
	v_add_u32_e32 v182, 64, v179
	s_cmp_eq_u32 s73, 0
	v_cndmask_b32_e64 v224, v142, v143, s[0:1]
	v_cndmask_b32_e64 v232, v142, v143, s[0:1]
	s_cselect_b64 vcc, -1, 0
	v_xor_b32_e32 v148, 16, v167
	s_and_b64 s[2:3], vcc, exec
	v_cndmask_b32_e32 v178, 1.0, v165, vcc
	v_cmp_lt_i32_e32 vcc, v148, v182
	v_cndmask_b32_e32 v148, v167, v148, vcc
	v_lshlrev_b32_e32 v184, 2, v148
	v_xor_b32_e32 v148, 32, v167
	v_cmp_lt_i32_e32 vcc, v148, v182
	v_cndmask_b32_e32 v148, v167, v148, vcc
	v_lshlrev_b32_e32 v183, 2, v148
	v_cndmask_b32_e64 v228, v136, v137, s[0:1]
	v_cndmask_b32_e64 v236, v136, v137, s[0:1]
	v_permlane32_swap_b32_e32 v126, v127
	v_cndmask_b32_e64 v240, v134, v135, s[0:1]
	v_pk_mul_f32 v[242:243], v[126:127], v[224:225] op_sel:[1,0] op_sel_hi:[0,0] neg_lo:[1,0]
	v_pk_fma_f32 v[186:187], v[126:127], v[240:241], v[242:243] op_sel_hi:[1,0,1]
	s_nop 1
	v_permlane32_swap_b32_e32 v186, v187
	v_permlane32_swap_b32_e32 v124, v125
	v_cndmask_b32_e64 v240, v132, v133, s[0:1]
	v_pk_mul_f32 v[242:243], v[124:125], v[226:227] op_sel:[1,0] op_sel_hi:[0,0] neg_lo:[1,0]
	v_pk_fma_f32 v[138:139], v[124:125], v[240:241], v[242:243] op_sel_hi:[1,0,1]
	s_nop 1
	v_permlane32_swap_b32_e32 v138, v139
	v_pk_mul_f32 v[194:195], v[178:179], v[186:187] op_sel_hi:[0,1]
	s_cselect_b32 s9, s17, s80
	s_cselect_b32 s8, s16, s79
	v_pk_mul_f32 v[138:139], v[178:179], v[138:139] op_sel_hi:[0,1]
	v_permlane32_swap_b32_e32 v120, v121
	v_cndmask_b32_e64 v240, v128, v129, s[0:1]
	v_pk_mul_f32 v[242:243], v[120:121], v[228:229] op_sel:[1,0] op_sel_hi:[0,0] neg_lo:[1,0]
	v_pk_fma_f32 v[140:141], v[120:121], v[240:241], v[242:243] op_sel_hi:[1,0,1]
	s_nop 1
	v_permlane32_swap_b32_e32 v140, v141
	v_permlane32_swap_b32_e32 v122, v123
	v_cndmask_b32_e64 v240, v130, v131, s[0:1]
	v_pk_mul_f32 v[242:243], v[122:123], v[230:231] op_sel:[1,0] op_sel_hi:[0,0] neg_lo:[1,0]
	v_pk_fma_f32 v[186:187], v[122:123], v[240:241], v[242:243] op_sel_hi:[1,0,1]
	s_nop 1
	v_permlane32_swap_b32_e32 v186, v187
	v_mov_b64_e32 v[136:137], s[8:9]
	s_lshl_b32 s62, s72, 8
	v_pk_mul_f32 v[192:193], v[178:179], v[186:187] op_sel_hi:[0,1]
	v_pk_mul_f32 v[140:141], v[178:179], v[140:141] op_sel_hi:[0,1]
	v_mul_f32_e32 v179, v139, v139
	v_mul_f32_e32 v185, v195, v195
	v_mad_i64_i32 v[136:137], s[2:3], v197, s20, v[136:137]
	s_ashr_i32 s63, s62, 31
	v_fmac_f32_e32 v179, v138, v138
	v_fmac_f32_e32 v185, v194, v194
	v_lshl_add_u64 v[136:137], s[62:63], 1, v[136:137]
	s_lshl_b32 s28, s34, 1
	v_add_f32_e32 v179, v179, v185
	v_mul_f32_e32 v185, v141, v141
	v_mul_f32_e32 v186, v193, v193
	v_lshl_add_u64 v[136:137], v[136:137], 0, s[28:29]
	v_lshlrev_b32_e32 v148, 1, v152
	v_fmac_f32_e32 v185, v140, v140
	v_fmac_f32_e32 v186, v192, v192
	v_lshl_add_u64 v[136:137], v[136:137], 0, v[148:149]
	v_add_f32_e32 v185, v185, v186
	v_cvt_pk_bf16_f32 v138, v138, v139
	v_cvt_pk_bf16_f32 v139, v194, v195
	v_add_f32_e32 v179, v179, v185
	v_cvt_pk_bf16_f32 v140, v140, v141
	v_cvt_pk_bf16_f32 v141, v192, v193
	global_store_dwordx4 v[136:137], v[138:141], off
	ds_bpermute_b32 v185, v184, v179
	s_waitcnt lgkmcnt(0)
	v_add_f32_e32 v185, v179, v185
	v_permlane32_swap_b32_e32 v94, v95
	v_cndmask_b32_e64 v240, v134, v135, s[0:1]
	v_pk_mul_f32 v[242:243], v[94:95], v[232:233] op_sel:[1,0] op_sel_hi:[0,0] neg_lo:[1,0]
	v_pk_fma_f32 v[134:135], v[94:95], v[240:241], v[242:243] op_sel_hi:[1,0,1]
	s_nop 1
	v_permlane32_swap_b32_e32 v134, v135
	v_permlane32_swap_b32_e32 v92, v93
	v_cndmask_b32_e64 v240, v132, v133, s[0:1]
	v_pk_mul_f32 v[242:243], v[92:93], v[234:235] op_sel:[1,0] op_sel_hi:[0,0] neg_lo:[1,0]
	v_pk_fma_f32 v[132:133], v[92:93], v[240:241], v[242:243] op_sel_hi:[1,0,1]
	s_nop 1
	v_permlane32_swap_b32_e32 v132, v133
	v_pk_mul_f32 v[134:135], v[178:179], v[134:135] op_sel_hi:[0,1]
	v_pk_mul_f32 v[132:133], v[178:179], v[132:133] op_sel_hi:[0,1]
	v_permlane32_swap_b32_e32 v88, v89
	v_cndmask_b32_e64 v240, v128, v129, s[0:1]
	v_pk_mul_f32 v[242:243], v[88:89], v[236:237] op_sel:[1,0] op_sel_hi:[0,0] neg_lo:[1,0]
	v_pk_fma_f32 v[128:129], v[88:89], v[240:241], v[242:243] op_sel_hi:[1,0,1]
	s_nop 1
	v_permlane32_swap_b32_e32 v128, v129
	v_permlane32_swap_b32_e32 v90, v91
	v_cndmask_b32_e64 v240, v130, v131, s[0:1]
	v_pk_mul_f32 v[242:243], v[90:91], v[238:239] op_sel:[1,0] op_sel_hi:[0,0] neg_lo:[1,0]
	v_pk_fma_f32 v[130:131], v[90:91], v[240:241], v[242:243] op_sel_hi:[1,0,1]
	s_nop 1
	v_permlane32_swap_b32_e32 v130, v131
	v_or_b32_e32 v180, 16, v197
	v_pk_mul_f32 v[138:139], v[178:179], v[130:131] op_sel_hi:[0,1]
	v_pk_mul_f32 v[130:131], v[178:179], v[128:129] op_sel_hi:[0,1]
	v_mul_f32_e32 v128, v133, v133
	v_mul_f32_e32 v129, v135, v135
	v_fmac_f32_e32 v128, v132, v132
	v_fmac_f32_e32 v129, v134, v134
	v_add_f32_e32 v128, v128, v129
	v_mul_f32_e32 v129, v131, v131
	v_mul_f32_e32 v140, v139, v139
	v_fmac_f32_e32 v129, v130, v130
	v_fmac_f32_e32 v140, v138, v138
	v_add_f32_e32 v129, v129, v140
	v_add_f32_e32 v128, v128, v129
	ds_bpermute_b32 v129, v184, v128
	ds_bpermute_b32 v186, v183, v185
	v_cmp_lt_i32_e32 vcc, s97, v180
	s_waitcnt lgkmcnt(1)
	v_add_f32_e32 v187, v128, v129
	v_cvt_pk_bf16_f32 v128, v132, v133
	v_cvt_pk_bf16_f32 v129, v134, v135
	v_cvt_pk_bf16_f32 v130, v130, v131
	v_cvt_pk_bf16_f32 v131, v138, v139
	global_store_dwordx4 v[136:137], v[128:131], off offset:256
	v_mov_b32_e32 v137, v149
	ds_bpermute_b32 v188, v183, v187
	v_mov_b32_e32 v128, s45
	v_cndmask_b32_e64 v128, v180, v128, s[10:11]
	v_lshlrev_b32_e32 v128, 6, v128
	v_and_b32_e32 v136, 0xfc0, v128
	v_lshl_add_u64 v[132:133], v[168:169], 0, v[136:137]
	v_lshl_add_u64 v[140:141], v[170:171], 0, v[136:137]
	global_load_dwordx4 v[128:131], v[132:133], off offset:16
	s_nop 0
	global_load_dwordx4 v[132:135], v[132:133], off
	s_nop 0
	global_load_dwordx4 v[136:139], v[140:141], off offset:16
	s_nop 0
	global_load_dwordx4 v[140:143], v[140:141], off
	s_and_saveexec_b64 s[2:3], vcc
	s_cbranch_execz .LBB0_678
	s_waitcnt vmcnt(3)
	v_mov_b32_e32 v128, 1.0
	s_waitcnt vmcnt(1)
	v_mov_b32_e32 v136, 0
	v_mov_b32_e32 v137, v136
	v_mov_b32_e32 v138, v136
	v_mov_b32_e32 v139, v136
	s_waitcnt vmcnt(0)
	v_mov_b32_e32 v140, v136
	v_mov_b32_e32 v141, v136
	v_mov_b32_e32 v142, v136
	v_mov_b32_e32 v143, v136
	v_mov_b32_e32 v129, v128
	v_mov_b32_e32 v130, v128
	v_mov_b32_e32 v131, v128
	v_mov_b32_e32 v132, v128
	v_mov_b32_e32 v133, v128
	v_mov_b32_e32 v134, v128
	v_mov_b32_e32 v135, v128
; __device__ __forceinline__ unsigned cvt_pk_bf16(float lo, float hi) { unsigned r; asm volatile("v_cvt_pk_bf16_f32 %0, %1, %2" : "=v"(r) : "v"(lo), "v"(hi)); return r; }
;     __device__ __forceinline__ void operator()(const f32x4 (&acc)[2][2][4][2], const Unit& u, int wr, int wc, int fr, int fq) const {
;     ...
;                 for (int m = 0; m < 4; ++m) {
;                     const int row = u.pm * BM + ai * HALF + wr * 64 + m * 16 + fr;
;                     const bool lat = row < MLAT; const int t = row & (SEQ - 1); const int pos = axis ? (t & 63) : (t >> 6);
;                     f32x4 c0 = *(const f32x4*)(ropec + pos * 16 + pb), c1 = *(const f32x4*)(ropec + pos * 16 + pb + 4), s0 = *(const f32x4*)(ropes + pos * 16 + pb), s1 = *(const f32x4*)(ropes + pos * 16 + pb + 4);
;                     if (!lat) { c0 = (f32x4){1.f, 1.f, 1.f, 1.f}; c1 = c0; s0 = (f32x4){0.f, 0.f, 0.f, 0.f}; s1 = s0; }
;                     if (!upper) { s0 = -s0; s1 = -s1; }
;                     bf16_t* rowp = dst + (size_t)row * DQK + u.pn * BM + wc * 32 + 8 * fq;
; #pragma unroll
;                     for (int bj = 0; bj < 2; ++bj) { const f32x4 a0 = acc[ai][bj][m][0], a1 = acc[ai][bj][m][1]; f32x4 p0, p1;
; #pragma unroll
;                         for (int i = 0; i < 4; ++i) {
;                             auto r0 = __builtin_amdgcn_permlane32_swap(__float_as_uint(a0[i]), __float_as_uint(a0[i]), false, false); p0[i] = __uint_as_float(upper ? r0[0] : r0[1]);
;                             auto r1 = __builtin_amdgcn_permlane32_swap(__float_as_uint(a1[i]), __float_as_uint(a1[i]), false, false); p1[i] = __uint_as_float(upper ? r1[0] : r1[1]); }
;                         const f32x4 o0 = (a0 * c0 + p0 * s0) * sc, o1 = (a1 * c1 + p1 * s1) * sc;
;                         { float ss = ((o0[0] * o0[0] + o0[1] * o0[1]) + (o0[2] * o0[2] + o0[3] * o0[3])) + ((o1[0] * o1[0] + o1[1] * o1[1]) + (o1[2] * o1[2] + o1[3] * o1[3]));
;                           ss += __shfl_xor(ss, 16); ss += __shfl_xor(ss, 32); gmax = fmaxf(gmax, ss); }
;                         u32x4 w; w.x = cvt_pk_bf16(o0[0], o0[1]); w.y = cvt_pk_bf16(o0[2], o0[3]); w.z = cvt_pk_bf16(o1[0], o1[1]); w.w = cvt_pk_bf16(o1[2], o1[3]);
;                         *(u32x4*)(rowp + bj * HALF) = w; }
.LBB0_678:
	s_or_b64 exec, exec, s[2:3]
	s_waitcnt vmcnt(1)
	v_cndmask_b32_e64 v228, v138, v139, s[0:1]
	v_cndmask_b32_e64 v238, v138, v139, s[0:1]
	s_waitcnt vmcnt(0)
	v_cndmask_b32_e64 v224, v140, v141, s[0:1]
	v_cndmask_b32_e64 v234, v140, v141, s[0:1]
	v_cndmask_b32_e64 v230, v136, v137, s[0:1]
	v_cndmask_b32_e64 v236, v136, v137, s[0:1]
	v_mov_b64_e32 v[136:137], s[8:9]
	v_mad_i64_i32 v[136:137], s[2:3], v180, s20, v[136:137]
	v_cndmask_b32_e64 v226, v142, v143, s[0:1]
	v_cndmask_b32_e64 v232, v142, v143, s[0:1]
	v_mov_b32_e32 v179, v178
	v_permlane32_swap_b32_e32 v116, v117
	v_cndmask_b32_e64 v240, v132, v133, s[0:1]
	v_pk_mul_f32 v[242:243], v[116:117], v[224:225] op_sel:[1,0] op_sel_hi:[0,0] neg_lo:[1,0]
	v_pk_fma_f32 v[138:139], v[116:117], v[240:241], v[242:243] op_sel_hi:[1,0,1]
	s_nop 1
	v_permlane32_swap_b32_e32 v138, v139
	v_permlane32_swap_b32_e32 v118, v119
	v_cndmask_b32_e64 v240, v134, v135, s[0:1]
	v_pk_mul_f32 v[242:243], v[118:119], v[226:227] op_sel:[1,0] op_sel_hi:[0,0] neg_lo:[1,0]
	v_pk_fma_f32 v[202:203], v[118:119], v[240:241], v[242:243] op_sel_hi:[1,0,1]
	s_nop 1
	v_permlane32_swap_b32_e32 v202, v203
	v_mov_b32_e32 v180, v178
	v_mov_b32_e32 v181, v178
	v_pk_mul_f32 v[202:203], v[180:181], v[202:203]
	v_pk_mul_f32 v[138:139], v[178:179], v[138:139]
	v_permlane32_swap_b32_e32 v114, v115
	v_cndmask_b32_e64 v240, v130, v131, s[0:1]
	v_pk_mul_f32 v[242:243], v[114:115], v[228:229] op_sel:[1,0] op_sel_hi:[0,0] neg_lo:[1,0]
	v_pk_fma_f32 v[190:191], v[114:115], v[240:241], v[242:243] op_sel_hi:[1,0,1]
	s_nop 1
	v_permlane32_swap_b32_e32 v190, v191
	v_lshl_add_u64 v[136:137], s[62:63], 1, v[136:137]
	v_permlane32_swap_b32_e32 v112, v113
	v_cndmask_b32_e64 v240, v128, v129, s[0:1]
	v_pk_mul_f32 v[242:243], v[112:113], v[230:231] op_sel:[1,0] op_sel_hi:[0,0] neg_lo:[1,0]
	v_pk_fma_f32 v[140:141], v[112:113], v[240:241], v[242:243] op_sel_hi:[1,0,1]
	s_nop 1
	v_permlane32_swap_b32_e32 v140, v141
	v_pk_mul_f32 v[204:205], v[180:181], v[190:191]
	v_mul_f32_e32 v189, v139, v139
	v_mul_f32_e32 v190, v203, v203
	v_lshl_add_u64 v[136:137], v[136:137], 0, s[28:29]
	v_pk_mul_f32 v[140:141], v[178:179], v[140:141]
	v_fmac_f32_e32 v189, v138, v138
	v_fmac_f32_e32 v190, v202, v202
	v_lshl_add_u64 v[136:137], v[136:137], 0, v[148:149]
	v_add_f32_e32 v189, v189, v190
	v_mul_f32_e32 v190, v141, v141
	v_cvt_pk_bf16_f32 v138, v138, v139
	v_cvt_pk_bf16_f32 v139, v202, v203
	v_fmac_f32_e32 v190, v140, v140
	v_cvt_pk_bf16_f32 v140, v140, v141
	v_cvt_pk_bf16_f32 v141, v204, v205
	global_store_dwordx4 v[136:137], v[138:141], off
	v_mul_f32_e32 v191, v205, v205
	v_fmac_f32_e32 v191, v204, v204
	v_add_f32_e32 v190, v190, v191
	v_permlane32_swap_b32_e32 v86, v87
	v_cndmask_b32_e64 v240, v134, v135, s[0:1]
	v_pk_mul_f32 v[242:243], v[86:87], v[232:233] op_sel:[1,0] op_sel_hi:[0,0] neg_lo:[1,0]
	v_pk_fma_f32 v[134:135], v[86:87], v[240:241], v[242:243] op_sel_hi:[1,0,1]
	s_nop 1
	v_permlane32_swap_b32_e32 v134, v135
	v_permlane32_swap_b32_e32 v84, v85
	v_cndmask_b32_e64 v240, v132, v133, s[0:1]
	v_pk_mul_f32 v[242:243], v[84:85], v[234:235] op_sel:[1,0] op_sel_hi:[0,0] neg_lo:[1,0]
	v_pk_fma_f32 v[132:133], v[84:85], v[240:241], v[242:243] op_sel_hi:[1,0,1]
	s_nop 1
	v_permlane32_swap_b32_e32 v132, v133
	v_pk_mul_f32 v[134:135], v[180:181], v[134:135]
	v_pk_mul_f32 v[132:133], v[178:179], v[132:133]
	v_permlane32_swap_b32_e32 v80, v81
	v_cndmask_b32_e64 v240, v128, v129, s[0:1]
	v_pk_mul_f32 v[242:243], v[80:81], v[236:237] op_sel:[1,0] op_sel_hi:[0,0] neg_lo:[1,0]
	v_pk_fma_f32 v[128:129], v[80:81], v[240:241], v[242:243] op_sel_hi:[1,0,1]
	s_nop 1
	v_permlane32_swap_b32_e32 v128, v129
	v_permlane32_swap_b32_e32 v82, v83
	v_cndmask_b32_e64 v240, v130, v131, s[0:1]
	v_pk_mul_f32 v[242:243], v[82:83], v[238:239] op_sel:[1,0] op_sel_hi:[0,0] neg_lo:[1,0]
	v_pk_fma_f32 v[130:131], v[82:83], v[240:241], v[242:243] op_sel_hi:[1,0,1]
	s_nop 1
	v_permlane32_swap_b32_e32 v130, v131
	v_or_b32_e32 v193, 32, v197
	v_pk_mul_f32 v[138:139], v[180:181], v[130:131]
	v_pk_mul_f32 v[130:131], v[178:179], v[128:129]
	v_mul_f32_e32 v128, v133, v133
	v_mul_f32_e32 v129, v135, v135
	v_fmac_f32_e32 v128, v132, v132
	v_fmac_f32_e32 v129, v134, v134
	v_add_f32_e32 v128, v128, v129
	v_mul_f32_e32 v129, v131, v131
	v_mul_f32_e32 v140, v139, v139
	v_fmac_f32_e32 v129, v130, v130
	v_fmac_f32_e32 v140, v138, v138
	v_add_f32_e32 v129, v129, v140
	v_add_f32_e32 v128, v128, v129
	ds_bpermute_b32 v129, v184, v128
	v_add_f32_e32 v189, v189, v190
	ds_bpermute_b32 v190, v184, v189
	v_cmp_lt_i32_e32 vcc, s97, v193
	s_waitcnt lgkmcnt(1)
	v_add_f32_e32 v191, v128, v129
	v_cvt_pk_bf16_f32 v128, v132, v133
	v_cvt_pk_bf16_f32 v129, v134, v135
	v_cvt_pk_bf16_f32 v130, v130, v131
	v_cvt_pk_bf16_f32 v131, v138, v139
	global_store_dwordx4 v[136:137], v[128:131], off offset:256
	v_mov_b32_e32 v137, v149
	s_waitcnt lgkmcnt(0)
	v_add_f32_e32 v189, v189, v190
	v_mov_b32_e32 v128, s45
	v_cndmask_b32_e64 v128, v193, v128, s[10:11]
	v_lshlrev_b32_e32 v128, 6, v128
	v_and_b32_e32 v136, 0xfc0, v128
	v_lshl_add_u64 v[132:133], v[168:169], 0, v[136:137]
	v_lshl_add_u64 v[140:141], v[170:171], 0, v[136:137]
	global_load_dwordx4 v[128:131], v[132:133], off offset:16
	s_nop 0
	global_load_dwordx4 v[132:135], v[132:133], off
	s_nop 0
	global_load_dwordx4 v[136:139], v[140:141], off offset:16
	s_nop 0
	global_load_dwordx4 v[140:143], v[140:141], off
	ds_bpermute_b32 v190, v183, v189
	ds_bpermute_b32 v192, v183, v191
	s_and_saveexec_b64 s[2:3], vcc
	s_cbranch_execz .LBB0_680
	s_waitcnt vmcnt(3)
	v_mov_b32_e32 v128, 1.0
	s_waitcnt vmcnt(1)
	v_mov_b32_e32 v136, 0
	v_mov_b32_e32 v137, v136
	v_mov_b32_e32 v138, v136
	v_mov_b32_e32 v139, v136
	s_waitcnt vmcnt(0)
	v_mov_b32_e32 v140, v136
	v_mov_b32_e32 v141, v136
	v_mov_b32_e32 v142, v136
	v_mov_b32_e32 v143, v136
	v_mov_b32_e32 v129, v128
	v_mov_b32_e32 v130, v128
	v_mov_b32_e32 v131, v128
	v_mov_b32_e32 v132, v128
	v_mov_b32_e32 v133, v128
	v_mov_b32_e32 v134, v128
	v_mov_b32_e32 v135, v128
; __device__ __forceinline__ unsigned cvt_pk_bf16(float lo, float hi) { unsigned r; asm volatile("v_cvt_pk_bf16_f32 %0, %1, %2" : "=v"(r) : "v"(lo), "v"(hi)); return r; }
;     __device__ __forceinline__ void operator()(const f32x4 (&acc)[2][2][4][2], const Unit& u, int wr, int wc, int fr, int fq) const {
;     ...
;                 for (int m = 0; m < 4; ++m) {
;                     const int row = u.pm * BM + ai * HALF + wr * 64 + m * 16 + fr;
;                     const bool lat = row < MLAT; const int t = row & (SEQ - 1); const int pos = axis ? (t & 63) : (t >> 6);
;                     f32x4 c0 = *(const f32x4*)(ropec + pos * 16 + pb), c1 = *(const f32x4*)(ropec + pos * 16 + pb + 4), s0 = *(const f32x4*)(ropes + pos * 16 + pb), s1 = *(const f32x4*)(ropes + pos * 16 + pb + 4);
;                     if (!lat) { c0 = (f32x4){1.f, 1.f, 1.f, 1.f}; c1 = c0; s0 = (f32x4){0.f, 0.f, 0.f, 0.f}; s1 = s0; }
;                     if (!upper) { s0 = -s0; s1 = -s1; }
;                     bf16_t* rowp = dst + (size_t)row * DQK + u.pn * BM + wc * 32 + 8 * fq;
; #pragma unroll
;                     for (int bj = 0; bj < 2; ++bj) { const f32x4 a0 = acc[ai][bj][m][0], a1 = acc[ai][bj][m][1]; f32x4 p0, p1;
; #pragma unroll
;                         for (int i = 0; i < 4; ++i) {
;                             auto r0 = __builtin_amdgcn_permlane32_swap(__float_as_uint(a0[i]), __float_as_uint(a0[i]), false, false); p0[i] = __uint_as_float(upper ? r0[0] : r0[1]);
;                             auto r1 = __builtin_amdgcn_permlane32_swap(__float_as_uint(a1[i]), __float_as_uint(a1[i]), false, false); p1[i] = __uint_as_float(upper ? r1[0] : r1[1]); }
;                         const f32x4 o0 = (a0 * c0 + p0 * s0) * sc, o1 = (a1 * c1 + p1 * s1) * sc;
;                         { float ss = ((o0[0] * o0[0] + o0[1] * o0[1]) + (o0[2] * o0[2] + o0[3] * o0[3])) + ((o1[0] * o1[0] + o1[1] * o1[1]) + (o1[2] * o1[2] + o1[3] * o1[3]));
;                           ss += __shfl_xor(ss, 16); ss += __shfl_xor(ss, 32); gmax = fmaxf(gmax, ss); }
;                         u32x4 w; w.x = cvt_pk_bf16(o0[0], o0[1]); w.y = cvt_pk_bf16(o0[2], o0[3]); w.z = cvt_pk_bf16(o1[0], o1[1]); w.w = cvt_pk_bf16(o1[2], o1[3]);
;                         *(u32x4*)(rowp + bj * HALF) = w; }
.LBB0_680:
	s_or_b64 exec, exec, s[2:3]
	s_waitcnt vmcnt(1)
	v_cndmask_b32_e64 v228, v138, v139, s[0:1]
	v_cndmask_b32_e64 v238, v138, v139, s[0:1]
	s_waitcnt vmcnt(0)
	v_cndmask_b32_e64 v226, v140, v141, s[0:1]
	v_cndmask_b32_e64 v234, v140, v141, s[0:1]
	v_cndmask_b32_e64 v230, v136, v137, s[0:1]
	v_cndmask_b32_e64 v236, v136, v137, s[0:1]
	v_mov_b64_e32 v[136:137], s[8:9]
	v_mad_i64_i32 v[136:137], s[2:3], v193, s20, v[136:137]
	v_cndmask_b32_e64 v224, v142, v143, s[0:1]
	v_cndmask_b32_e64 v232, v142, v143, s[0:1]
	v_permlane32_swap_b32_e32 v110, v111
	v_cndmask_b32_e64 v240, v134, v135, s[0:1]
	v_pk_mul_f32 v[242:243], v[110:111], v[224:225] op_sel:[1,0] op_sel_hi:[0,0] neg_lo:[1,0]
	v_pk_fma_f32 v[194:195], v[110:111], v[240:241], v[242:243] op_sel_hi:[1,0,1]
	s_nop 1
	v_permlane32_swap_b32_e32 v194, v195
	v_permlane32_swap_b32_e32 v108, v109
	v_cndmask_b32_e64 v240, v132, v133, s[0:1]
	v_pk_mul_f32 v[242:243], v[108:109], v[226:227] op_sel:[1,0] op_sel_hi:[0,0] neg_lo:[1,0]
	v_pk_fma_f32 v[138:139], v[108:109], v[240:241], v[242:243] op_sel_hi:[1,0,1]
	s_nop 1
	v_permlane32_swap_b32_e32 v138, v139
	v_pk_mul_f32 v[208:209], v[180:181], v[194:195]
	v_pk_mul_f32 v[138:139], v[178:179], v[138:139]
	v_permlane32_swap_b32_e32 v106, v107
	v_cndmask_b32_e64 v240, v130, v131, s[0:1]
	v_pk_mul_f32 v[242:243], v[106:107], v[228:229] op_sel:[1,0] op_sel_hi:[0,0] neg_lo:[1,0]
	v_pk_fma_f32 v[194:195], v[106:107], v[240:241], v[242:243] op_sel_hi:[1,0,1]
	s_nop 1
	v_permlane32_swap_b32_e32 v194, v195
	v_lshl_add_u64 v[136:137], s[62:63], 1, v[136:137]
	v_permlane32_swap_b32_e32 v104, v105
	v_cndmask_b32_e64 v240, v128, v129, s[0:1]
	v_pk_mul_f32 v[242:243], v[104:105], v[230:231] op_sel:[1,0] op_sel_hi:[0,0] neg_lo:[1,0]
	v_pk_fma_f32 v[140:141], v[104:105], v[240:241], v[242:243] op_sel_hi:[1,0,1]
	s_nop 1
	v_permlane32_swap_b32_e32 v140, v141
	v_pk_mul_f32 v[206:207], v[180:181], v[194:195]
	v_mul_f32_e32 v193, v139, v139
	v_mul_f32_e32 v194, v209, v209
	v_lshl_add_u64 v[136:137], v[136:137], 0, s[28:29]
	v_pk_mul_f32 v[140:141], v[178:179], v[140:141]
	v_fmac_f32_e32 v193, v138, v138
	v_fmac_f32_e32 v194, v208, v208
	v_lshl_add_u64 v[136:137], v[136:137], 0, v[148:149]
	v_add_f32_e32 v193, v193, v194
	v_mul_f32_e32 v194, v141, v141
	v_cvt_pk_bf16_f32 v138, v138, v139
	v_cvt_pk_bf16_f32 v139, v208, v209
	v_fmac_f32_e32 v194, v140, v140
	v_cvt_pk_bf16_f32 v140, v140, v141
	v_cvt_pk_bf16_f32 v141, v206, v207
	global_store_dwordx4 v[136:137], v[138:141], off
	v_mul_f32_e32 v195, v207, v207
	v_fmac_f32_e32 v195, v206, v206
	v_add_f32_e32 v194, v194, v195
	v_permlane32_swap_b32_e32 v78, v79
	v_cndmask_b32_e64 v240, v134, v135, s[0:1]
	v_pk_mul_f32 v[242:243], v[78:79], v[232:233] op_sel:[1,0] op_sel_hi:[0,0] neg_lo:[1,0]
	v_pk_fma_f32 v[134:135], v[78:79], v[240:241], v[242:243] op_sel_hi:[1,0,1]
	s_nop 1
	v_permlane32_swap_b32_e32 v134, v135
	v_permlane32_swap_b32_e32 v76, v77
	v_cndmask_b32_e64 v240, v132, v133, s[0:1]
	v_pk_mul_f32 v[242:243], v[76:77], v[234:235] op_sel:[1,0] op_sel_hi:[0,0] neg_lo:[1,0]
	v_pk_fma_f32 v[132:133], v[76:77], v[240:241], v[242:243] op_sel_hi:[1,0,1]
	s_nop 1
	v_permlane32_swap_b32_e32 v132, v133
	v_pk_mul_f32 v[134:135], v[180:181], v[134:135]
	v_pk_mul_f32 v[132:133], v[178:179], v[132:133]
	v_permlane32_swap_b32_e32 v72, v73
	v_cndmask_b32_e64 v240, v128, v129, s[0:1]
	v_pk_mul_f32 v[242:243], v[72:73], v[236:237] op_sel:[1,0] op_sel_hi:[0,0] neg_lo:[1,0]
	v_pk_fma_f32 v[128:129], v[72:73], v[240:241], v[242:243] op_sel_hi:[1,0,1]
	s_nop 1
	v_permlane32_swap_b32_e32 v128, v129
	v_permlane32_swap_b32_e32 v74, v75
	v_cndmask_b32_e64 v240, v130, v131, s[0:1]
	v_pk_mul_f32 v[242:243], v[74:75], v[238:239] op_sel:[1,0] op_sel_hi:[0,0] neg_lo:[1,0]
	v_pk_fma_f32 v[130:131], v[74:75], v[240:241], v[242:243] op_sel_hi:[1,0,1]
	s_nop 1
	v_permlane32_swap_b32_e32 v130, v131
	v_add_f32_e32 v193, v193, v194
	v_pk_mul_f32 v[138:139], v[180:181], v[130:131]
	v_pk_mul_f32 v[130:131], v[178:179], v[128:129]
	v_mul_f32_e32 v128, v133, v133
	v_mul_f32_e32 v129, v135, v135
	v_fmac_f32_e32 v128, v132, v132
	v_fmac_f32_e32 v129, v134, v134
	v_add_f32_e32 v128, v128, v129
	v_mul_f32_e32 v129, v131, v131
	v_mul_f32_e32 v140, v139, v139
	v_fmac_f32_e32 v129, v130, v130
	v_fmac_f32_e32 v140, v138, v138
	v_add_f32_e32 v129, v129, v140
	v_add_f32_e32 v128, v128, v129
	ds_bpermute_b32 v129, v184, v128
	v_or_b32_e32 v180, 48, v197
	ds_bpermute_b32 v194, v184, v193
	v_cmp_lt_i32_e32 vcc, s97, v180
	s_waitcnt lgkmcnt(1)
	v_add_f32_e32 v195, v128, v129
	v_cvt_pk_bf16_f32 v128, v132, v133
	v_cvt_pk_bf16_f32 v129, v134, v135
	v_cvt_pk_bf16_f32 v130, v130, v131
	v_cvt_pk_bf16_f32 v131, v138, v139
	global_store_dwordx4 v[136:137], v[128:131], off offset:256
	v_mov_b32_e32 v137, v149
	s_waitcnt lgkmcnt(0)
	v_add_f32_e32 v193, v193, v194
	v_mov_b32_e32 v128, s45
	v_cndmask_b32_e64 v128, v180, v128, s[10:11]
	v_lshlrev_b32_e32 v128, 6, v128
	v_and_b32_e32 v136, 0xfc0, v128
	v_lshl_add_u64 v[132:133], v[168:169], 0, v[136:137]
	v_lshl_add_u64 v[140:141], v[170:171], 0, v[136:137]
	global_load_dwordx4 v[128:131], v[132:133], off offset:16
	s_nop 0
	global_load_dwordx4 v[132:135], v[132:133], off
	s_nop 0
	global_load_dwordx4 v[136:139], v[140:141], off offset:16
	s_nop 0
	global_load_dwordx4 v[140:143], v[140:141], off
	ds_bpermute_b32 v194, v183, v193
	ds_bpermute_b32 v196, v183, v195
	s_and_saveexec_b64 s[2:3], vcc
	s_cbranch_execz .LBB0_682
	s_waitcnt vmcnt(3)
	v_mov_b32_e32 v128, 1.0
	s_waitcnt vmcnt(1)
	v_mov_b32_e32 v136, 0
	v_mov_b32_e32 v137, v136
	v_mov_b32_e32 v138, v136
	v_mov_b32_e32 v139, v136
	s_waitcnt vmcnt(0)
	v_mov_b32_e32 v140, v136
	v_mov_b32_e32 v141, v136
	v_mov_b32_e32 v142, v136
	v_mov_b32_e32 v143, v136
	v_mov_b32_e32 v129, v128
	v_mov_b32_e32 v130, v128
	v_mov_b32_e32 v131, v128
	v_mov_b32_e32 v132, v128
	v_mov_b32_e32 v133, v128
	v_mov_b32_e32 v134, v128
	v_mov_b32_e32 v135, v128
; __device__ __forceinline__ unsigned cvt_pk_bf16(float lo, float hi) { unsigned r; asm volatile("v_cvt_pk_bf16_f32 %0, %1, %2" : "=v"(r) : "v"(lo), "v"(hi)); return r; }
;     __device__ __forceinline__ void operator()(const f32x4 (&acc)[2][2][4][2], const Unit& u, int wr, int wc, int fr, int fq) const {
;     ...
;                 for (int m = 0; m < 4; ++m) {
;                     const int row = u.pm * BM + ai * HALF + wr * 64 + m * 16 + fr;
;                     const bool lat = row < MLAT; const int t = row & (SEQ - 1); const int pos = axis ? (t & 63) : (t >> 6);
;                     f32x4 c0 = *(const f32x4*)(ropec + pos * 16 + pb), c1 = *(const f32x4*)(ropec + pos * 16 + pb + 4), s0 = *(const f32x4*)(ropes + pos * 16 + pb), s1 = *(const f32x4*)(ropes + pos * 16 + pb + 4);
;                     if (!lat) { c0 = (f32x4){1.f, 1.f, 1.f, 1.f}; c1 = c0; s0 = (f32x4){0.f, 0.f, 0.f, 0.f}; s1 = s0; }
;                     if (!upper) { s0 = -s0; s1 = -s1; }
;                     bf16_t* rowp = dst + (size_t)row * DQK + u.pn * BM + wc * 32 + 8 * fq;
; #pragma unroll
;                     for (int bj = 0; bj < 2; ++bj) { const f32x4 a0 = acc[ai][bj][m][0], a1 = acc[ai][bj][m][1]; f32x4 p0, p1;
; #pragma unroll
;                         for (int i = 0; i < 4; ++i) {
;                             auto r0 = __builtin_amdgcn_permlane32_swap(__float_as_uint(a0[i]), __float_as_uint(a0[i]), false, false); p0[i] = __uint_as_float(upper ? r0[0] : r0[1]);
;                             auto r1 = __builtin_amdgcn_permlane32_swap(__float_as_uint(a1[i]), __float_as_uint(a1[i]), false, false); p1[i] = __uint_as_float(upper ? r1[0] : r1[1]); }
;                         const f32x4 o0 = (a0 * c0 + p0 * s0) * sc, o1 = (a1 * c1 + p1 * s1) * sc;
;                         { float ss = ((o0[0] * o0[0] + o0[1] * o0[1]) + (o0[2] * o0[2] + o0[3] * o0[3])) + ((o1[0] * o1[0] + o1[1] * o1[1]) + (o1[2] * o1[2] + o1[3] * o1[3]));
;                           ss += __shfl_xor(ss, 16); ss += __shfl_xor(ss, 32); gmax = fmaxf(gmax, ss); }
;                         u32x4 w; w.x = cvt_pk_bf16(o0[0], o0[1]); w.y = cvt_pk_bf16(o0[2], o0[3]); w.z = cvt_pk_bf16(o1[0], o1[1]); w.w = cvt_pk_bf16(o1[2], o1[3]);
;                         *(u32x4*)(rowp + bj * HALF) = w; }
.LBB0_682:
	s_or_b64 exec, exec, s[2:3]
	s_waitcnt vmcnt(1)
	v_cndmask_b32_e64 v230, v136, v137, s[0:1]
	v_cndmask_b32_e64 v236, v136, v137, s[0:1]
	v_mov_b64_e32 v[136:137], s[8:9]
	v_mad_i64_i32 v[136:137], s[2:3], v180, s20, v[136:137]
	v_lshl_add_u64 v[136:137], s[62:63], 1, v[136:137]
	s_waitcnt vmcnt(0)
	v_lshl_add_u64 v[136:137], v[136:137], 0, s[28:29]
	v_cndmask_b32_e64 v224, v140, v141, s[0:1]
	v_cndmask_b32_e64 v234, v140, v141, s[0:1]
	v_lshl_add_u64 v[204:205], v[136:137], 0, v[148:149]
	v_cndmask_b32_e64 v228, v138, v139, s[0:1]
	v_cndmask_b32_e64 v238, v138, v139, s[0:1]
	v_cndmask_b32_e64 v226, v142, v143, s[0:1]
	v_cndmask_b32_e64 v232, v142, v143, s[0:1]
	v_permlane32_swap_b32_e32 v100, v101
	v_cndmask_b32_e64 v240, v132, v133, s[0:1]
	v_pk_mul_f32 v[242:243], v[100:101], v[224:225] op_sel:[1,0] op_sel_hi:[0,0] neg_lo:[1,0]
	v_pk_fma_f32 v[136:137], v[100:101], v[240:241], v[242:243] op_sel_hi:[1,0,1]
	s_nop 1
	v_permlane32_swap_b32_e32 v136, v137
	v_pk_mul_f32 v[210:211], v[178:179], v[136:137]
	v_permlane32_swap_b32_e32 v102, v103
	v_cndmask_b32_e64 v240, v134, v135, s[0:1]
	v_pk_mul_f32 v[242:243], v[102:103], v[226:227] op_sel:[1,0] op_sel_hi:[0,0] neg_lo:[1,0]
	v_pk_fma_f32 v[208:209], v[102:103], v[240:241], v[242:243] op_sel_hi:[1,0,1]
	s_nop 1
	v_permlane32_swap_b32_e32 v208, v209
	v_mov_b32_e32 v180, v178
	v_mov_b32_e32 v181, v178
	v_permlane32_swap_b32_e32 v98, v99
	v_cndmask_b32_e64 v240, v130, v131, s[0:1]
	v_pk_mul_f32 v[242:243], v[98:99], v[228:229] op_sel:[1,0] op_sel_hi:[0,0] neg_lo:[1,0]
	v_pk_fma_f32 v[136:137], v[98:99], v[240:241], v[242:243] op_sel_hi:[1,0,1]
	s_nop 1
	v_permlane32_swap_b32_e32 v136, v137
	v_pk_mul_f32 v[208:209], v[180:181], v[208:209]
	v_permlane32_swap_b32_e32 v96, v97
	v_cndmask_b32_e64 v240, v128, v129, s[0:1]
	v_pk_mul_f32 v[242:243], v[96:97], v[230:231] op_sel:[1,0] op_sel_hi:[0,0] neg_lo:[1,0]
	v_pk_fma_f32 v[138:139], v[96:97], v[240:241], v[242:243] op_sel_hi:[1,0,1]
	s_nop 1
	v_permlane32_swap_b32_e32 v138, v139
	v_pk_mul_f32 v[206:207], v[180:181], v[136:137]
	v_cvt_pk_bf16_f32 v136, v210, v211
	v_cvt_pk_bf16_f32 v137, v208, v209
	v_pk_mul_f32 v[212:213], v[178:179], v[138:139]
	v_cvt_pk_bf16_f32 v138, v212, v213
	v_cvt_pk_bf16_f32 v139, v206, v207
	global_store_dwordx4 v[204:205], v[136:139], off
	s_addk_i32 s44, 0x80
	v_permlane32_swap_b32_e32 v70, v71
	v_cndmask_b32_e64 v240, v134, v135, s[0:1]
	v_pk_mul_f32 v[242:243], v[70:71], v[232:233] op_sel:[1,0] op_sel_hi:[0,0] neg_lo:[1,0]
	v_pk_fma_f32 v[134:135], v[70:71], v[240:241], v[242:243] op_sel_hi:[1,0,1]
	s_nop 1
	v_permlane32_swap_b32_e32 v134, v135
	v_permlane32_swap_b32_e32 v68, v69
	v_cndmask_b32_e64 v240, v132, v133, s[0:1]
	v_pk_mul_f32 v[242:243], v[68:69], v[234:235] op_sel:[1,0] op_sel_hi:[0,0] neg_lo:[1,0]
	v_pk_fma_f32 v[132:133], v[68:69], v[240:241], v[242:243] op_sel_hi:[1,0,1]
	s_nop 1
	v_permlane32_swap_b32_e32 v132, v133
	v_pk_mul_f32 v[214:215], v[180:181], v[134:135]
	v_pk_mul_f32 v[218:219], v[178:179], v[132:133]
	v_permlane32_swap_b32_e32 v64, v65
	v_cndmask_b32_e64 v240, v128, v129, s[0:1]
	v_pk_mul_f32 v[242:243], v[64:65], v[236:237] op_sel:[1,0] op_sel_hi:[0,0] neg_lo:[1,0]
	v_pk_fma_f32 v[128:129], v[64:65], v[240:241], v[242:243] op_sel_hi:[1,0,1]
	s_nop 1
	v_permlane32_swap_b32_e32 v128, v129
	v_permlane32_swap_b32_e32 v66, v67
	v_cndmask_b32_e64 v240, v130, v131, s[0:1]
	v_pk_mul_f32 v[242:243], v[66:67], v[238:239] op_sel:[1,0] op_sel_hi:[0,0] neg_lo:[1,0]
	v_pk_fma_f32 v[130:131], v[66:67], v[240:241], v[242:243] op_sel_hi:[1,0,1]
	s_nop 1
	v_permlane32_swap_b32_e32 v130, v131
	v_pk_mul_f32 v[216:217], v[178:179], v[128:129]
	v_cvt_pk_bf16_f32 v128, v218, v219
	v_or_b32_e32 v202, s44, v159
	s_lshr_b32 s44, s44, 6
	v_pk_mul_f32 v[198:199], v[180:181], v[130:131]
	v_cvt_pk_bf16_f32 v129, v214, v215
	v_cvt_pk_bf16_f32 v130, v216, v217
	v_mov_b32_e32 v137, v149
	v_cvt_pk_bf16_f32 v131, v198, v199
	global_store_dwordx4 v[204:205], v[128:131], off offset:256
	v_mul_f32_e32 v197, v211, v211
	v_mul_f32_e32 v201, v209, v209
	v_mov_b32_e32 v128, s44
	v_cndmask_b32_e64 v128, v202, v128, s[10:11]
	v_lshlrev_b32_e32 v128, 6, v128
	v_and_b32_e32 v136, 0xfc0, v128
	v_lshl_add_u64 v[132:133], v[168:169], 0, v[136:137]
	v_lshl_add_u64 v[140:141], v[170:171], 0, v[136:137]
	global_load_dwordx4 v[128:131], v[132:133], off offset:16
	s_nop 0
	global_load_dwordx4 v[132:135], v[132:133], off
	s_nop 0
	global_load_dwordx4 v[136:139], v[140:141], off offset:16
	s_nop 0
	global_load_dwordx4 v[140:143], v[140:141], off
	v_fmac_f32_e32 v197, v210, v210
	v_fmac_f32_e32 v201, v208, v208
	v_add_f32_e32 v197, v197, v201
	v_mul_f32_e32 v201, v213, v213
	v_mul_f32_e32 v203, v207, v207
	v_fmac_f32_e32 v201, v212, v212
	v_fmac_f32_e32 v203, v206, v206
	v_add_f32_e32 v201, v201, v203
	v_mul_f32_e32 v203, v219, v219
	v_mul_f32_e32 v204, v215, v215
	v_fmac_f32_e32 v203, v218, v218
	v_fmac_f32_e32 v204, v214, v214
	v_add_f32_e32 v203, v203, v204
	v_mul_f32_e32 v204, v217, v217
	v_mul_f32_e32 v199, v199, v199
	v_fmac_f32_e32 v204, v216, v216
	v_fmac_f32_e32 v199, v198, v198
	v_add_f32_e32 v198, v204, v199
	v_add_f32_e32 v197, v197, v201
	v_add_f32_e32 v199, v203, v198
	ds_bpermute_b32 v201, v184, v197
	ds_bpermute_b32 v203, v184, v199
	v_cmp_lt_i32_e32 vcc, s97, v202
	s_waitcnt lgkmcnt(1)
	v_add_f32_e32 v197, v197, v201
	s_waitcnt lgkmcnt(0)
	v_add_f32_e32 v199, v199, v203
	ds_bpermute_b32 v198, v183, v197
	ds_bpermute_b32 v201, v183, v199
	s_and_saveexec_b64 s[2:3], vcc
	s_cbranch_execz .LBB0_684
	s_waitcnt vmcnt(3)
	v_mov_b32_e32 v128, 1.0
	s_waitcnt vmcnt(1)
	v_mov_b32_e32 v136, 0
	v_mov_b32_e32 v137, v136
	v_mov_b32_e32 v138, v136
	v_mov_b32_e32 v139, v136
	s_waitcnt vmcnt(0)
	v_mov_b32_e32 v140, v136
	v_mov_b32_e32 v141, v136
	v_mov_b32_e32 v142, v136
	v_mov_b32_e32 v143, v136
	v_mov_b32_e32 v129, v128
	v_mov_b32_e32 v130, v128
	v_mov_b32_e32 v131, v128
	v_mov_b32_e32 v132, v128
	v_mov_b32_e32 v133, v128
	v_mov_b32_e32 v134, v128
	v_mov_b32_e32 v135, v128
; __device__ __forceinline__ unsigned cvt_pk_bf16(float lo, float hi) { unsigned r; asm volatile("v_cvt_pk_bf16_f32 %0, %1, %2" : "=v"(r) : "v"(lo), "v"(hi)); return r; }
;     __device__ __forceinline__ void operator()(const f32x4 (&acc)[2][2][4][2], const Unit& u, int wr, int wc, int fr, int fq) const {
;     ...
;                 for (int m = 0; m < 4; ++m) {
;                     const int row = u.pm * BM + ai * HALF + wr * 64 + m * 16 + fr;
;                     const bool lat = row < MLAT; const int t = row & (SEQ - 1); const int pos = axis ? (t & 63) : (t >> 6);
;                     f32x4 c0 = *(const f32x4*)(ropec + pos * 16 + pb), c1 = *(const f32x4*)(ropec + pos * 16 + pb + 4), s0 = *(const f32x4*)(ropes + pos * 16 + pb), s1 = *(const f32x4*)(ropes + pos * 16 + pb + 4);
;                     if (!lat) { c0 = (f32x4){1.f, 1.f, 1.f, 1.f}; c1 = c0; s0 = (f32x4){0.f, 0.f, 0.f, 0.f}; s1 = s0; }
;                     if (!upper) { s0 = -s0; s1 = -s1; }
;                     bf16_t* rowp = dst + (size_t)row * DQK + u.pn * BM + wc * 32 + 8 * fq;
; #pragma unroll
;                     for (int bj = 0; bj < 2; ++bj) { const f32x4 a0 = acc[ai][bj][m][0], a1 = acc[ai][bj][m][1]; f32x4 p0, p1;
; #pragma unroll
;                         for (int i = 0; i < 4; ++i) {
;                             auto r0 = __builtin_amdgcn_permlane32_swap(__float_as_uint(a0[i]), __float_as_uint(a0[i]), false, false); p0[i] = __uint_as_float(upper ? r0[0] : r0[1]);
;                             auto r1 = __builtin_amdgcn_permlane32_swap(__float_as_uint(a1[i]), __float_as_uint(a1[i]), false, false); p1[i] = __uint_as_float(upper ? r1[0] : r1[1]); }
;                         const f32x4 o0 = (a0 * c0 + p0 * s0) * sc, o1 = (a1 * c1 + p1 * s1) * sc;
;                         { float ss = ((o0[0] * o0[0] + o0[1] * o0[1]) + (o0[2] * o0[2] + o0[3] * o0[3])) + ((o1[0] * o1[0] + o1[1] * o1[1]) + (o1[2] * o1[2] + o1[3] * o1[3]));
;                           ss += __shfl_xor(ss, 16); ss += __shfl_xor(ss, 32); gmax = fmaxf(gmax, ss); }
;                         u32x4 w; w.x = cvt_pk_bf16(o0[0], o0[1]); w.y = cvt_pk_bf16(o0[2], o0[3]); w.z = cvt_pk_bf16(o1[0], o1[1]); w.w = cvt_pk_bf16(o1[2], o1[3]);
;                         *(u32x4*)(rowp + bj * HALF) = w; }
.LBB0_684:
	s_or_b64 exec, exec, s[2:3]
	s_waitcnt vmcnt(1)
	v_cndmask_b32_e64 v228, v138, v139, s[0:1]
	v_cndmask_b32_e64 v236, v138, v139, s[0:1]
	s_waitcnt vmcnt(0)
	v_cndmask_b32_e64 v226, v140, v141, s[0:1]
	v_cndmask_b32_e64 v232, v140, v141, s[0:1]
	v_cndmask_b32_e64 v224, v142, v143, s[0:1]
	v_cndmask_b32_e64 v230, v142, v143, s[0:1]
	v_permlane32_swap_b32_e32 v62, v63
	v_cndmask_b32_e64 v240, v134, v135, s[0:1]
	v_pk_mul_f32 v[242:243], v[62:63], v[224:225] op_sel:[1,0] op_sel_hi:[0,0] neg_lo:[1,0]
	v_pk_fma_f32 v[204:205], v[62:63], v[240:241], v[242:243] op_sel_hi:[1,0,1]
	s_nop 1
	v_permlane32_swap_b32_e32 v204, v205
	v_cndmask_b32_e64 v224, v136, v137, s[0:1]
	v_cndmask_b32_e64 v234, v136, v137, s[0:1]
	v_mov_b64_e32 v[136:137], s[8:9]
	v_permlane32_swap_b32_e32 v60, v61
	v_cndmask_b32_e64 v240, v132, v133, s[0:1]
	v_pk_mul_f32 v[242:243], v[60:61], v[226:227] op_sel:[1,0] op_sel_hi:[0,0] neg_lo:[1,0]
	v_pk_fma_f32 v[138:139], v[60:61], v[240:241], v[242:243] op_sel_hi:[1,0,1]
	s_nop 1
	v_permlane32_swap_b32_e32 v138, v139
	v_pk_mul_f32 v[214:215], v[180:181], v[204:205]
	v_mad_i64_i32 v[136:137], s[2:3], v202, s20, v[136:137]
	v_pk_mul_f32 v[138:139], v[178:179], v[138:139]
	v_permlane32_swap_b32_e32 v58, v59
	v_cndmask_b32_e64 v240, v130, v131, s[0:1]
	v_pk_mul_f32 v[242:243], v[58:59], v[228:229] op_sel:[1,0] op_sel_hi:[0,0] neg_lo:[1,0]
	v_pk_fma_f32 v[204:205], v[58:59], v[240:241], v[242:243] op_sel_hi:[1,0,1]
	s_nop 1
	v_permlane32_swap_b32_e32 v204, v205
	v_lshl_add_u64 v[136:137], s[62:63], 1, v[136:137]
	v_permlane32_swap_b32_e32 v56, v57
	v_cndmask_b32_e64 v240, v128, v129, s[0:1]
	v_pk_mul_f32 v[242:243], v[56:57], v[224:225] op_sel:[1,0] op_sel_hi:[0,0] neg_lo:[1,0]
	v_pk_fma_f32 v[140:141], v[56:57], v[240:241], v[242:243] op_sel_hi:[1,0,1]
	s_nop 1
	v_permlane32_swap_b32_e32 v140, v141
	v_pk_mul_f32 v[212:213], v[180:181], v[204:205]
	v_mul_f32_e32 v203, v139, v139
	v_mul_f32_e32 v204, v215, v215
	v_lshl_add_u64 v[136:137], v[136:137], 0, s[28:29]
	v_pk_mul_f32 v[140:141], v[178:179], v[140:141]
	v_fmac_f32_e32 v203, v138, v138
	v_fmac_f32_e32 v204, v214, v214
	v_lshl_add_u64 v[136:137], v[136:137], 0, v[148:149]
	v_add_f32_e32 v203, v203, v204
	v_mul_f32_e32 v204, v141, v141
	v_cvt_pk_bf16_f32 v138, v138, v139
	v_cvt_pk_bf16_f32 v139, v214, v215
	v_fmac_f32_e32 v204, v140, v140
	v_cvt_pk_bf16_f32 v140, v140, v141
	v_cvt_pk_bf16_f32 v141, v212, v213
	global_store_dwordx4 v[136:137], v[138:141], off
	v_mul_f32_e32 v205, v213, v213
	v_fmac_f32_e32 v205, v212, v212
	v_add_f32_e32 v204, v204, v205
	v_permlane32_swap_b32_e32 v30, v31
	v_cndmask_b32_e64 v240, v134, v135, s[0:1]
	v_pk_mul_f32 v[242:243], v[30:31], v[230:231] op_sel:[1,0] op_sel_hi:[0,0] neg_lo:[1,0]
	v_pk_fma_f32 v[134:135], v[30:31], v[240:241], v[242:243] op_sel_hi:[1,0,1]
	s_nop 1
	v_permlane32_swap_b32_e32 v134, v135
	v_permlane32_swap_b32_e32 v28, v29
	v_cndmask_b32_e64 v240, v132, v133, s[0:1]
	v_pk_mul_f32 v[242:243], v[28:29], v[232:233] op_sel:[1,0] op_sel_hi:[0,0] neg_lo:[1,0]
	v_pk_fma_f32 v[132:133], v[28:29], v[240:241], v[242:243] op_sel_hi:[1,0,1]
	s_nop 1
	v_permlane32_swap_b32_e32 v132, v133
	v_pk_mul_f32 v[134:135], v[180:181], v[134:135]
	v_pk_mul_f32 v[132:133], v[178:179], v[132:133]
	v_permlane32_swap_b32_e32 v24, v25
	v_cndmask_b32_e64 v240, v128, v129, s[0:1]
	v_pk_mul_f32 v[242:243], v[24:25], v[234:235] op_sel:[1,0] op_sel_hi:[0,0] neg_lo:[1,0]
	v_pk_fma_f32 v[128:129], v[24:25], v[240:241], v[242:243] op_sel_hi:[1,0,1]
	s_nop 1
	v_permlane32_swap_b32_e32 v128, v129
	v_permlane32_swap_b32_e32 v26, v27
	v_cndmask_b32_e64 v240, v130, v131, s[0:1]
	v_pk_mul_f32 v[242:243], v[26:27], v[236:237] op_sel:[1,0] op_sel_hi:[0,0] neg_lo:[1,0]
	v_pk_fma_f32 v[130:131], v[26:27], v[240:241], v[242:243] op_sel_hi:[1,0,1]
	s_nop 1
	v_permlane32_swap_b32_e32 v130, v131
	v_add_f32_e32 v203, v203, v204
	v_pk_mul_f32 v[138:139], v[180:181], v[130:131]
	v_pk_mul_f32 v[130:131], v[178:179], v[128:129]
	v_mul_f32_e32 v128, v133, v133
	v_mul_f32_e32 v129, v135, v135
	v_fmac_f32_e32 v128, v132, v132
	v_fmac_f32_e32 v129, v134, v134
	v_add_f32_e32 v128, v128, v129
	v_mul_f32_e32 v129, v131, v131
	v_mul_f32_e32 v140, v139, v139
	v_fmac_f32_e32 v129, v130, v130
	v_fmac_f32_e32 v140, v138, v138
	v_add_f32_e32 v129, v129, v140
	v_add_f32_e32 v128, v128, v129
	ds_bpermute_b32 v129, v184, v128
	v_or_b32_e32 v180, 16, v202
	ds_bpermute_b32 v204, v184, v203
	v_cmp_lt_i32_e32 vcc, s97, v180
	s_waitcnt lgkmcnt(1)
	v_add_f32_e32 v205, v128, v129
	v_cvt_pk_bf16_f32 v128, v132, v133
	v_cvt_pk_bf16_f32 v129, v134, v135
	v_cvt_pk_bf16_f32 v130, v130, v131
	v_cvt_pk_bf16_f32 v131, v138, v139
	global_store_dwordx4 v[136:137], v[128:131], off offset:256
	v_mov_b32_e32 v137, v149
	s_waitcnt lgkmcnt(0)
	v_add_f32_e32 v203, v203, v204
	v_mov_b32_e32 v128, s44
	v_cndmask_b32_e64 v128, v180, v128, s[10:11]
	v_lshlrev_b32_e32 v128, 6, v128
	v_and_b32_e32 v136, 0xfc0, v128
	v_lshl_add_u64 v[132:133], v[168:169], 0, v[136:137]
	v_lshl_add_u64 v[140:141], v[170:171], 0, v[136:137]
	global_load_dwordx4 v[128:131], v[132:133], off offset:16
	s_nop 0
	global_load_dwordx4 v[132:135], v[132:133], off
	s_nop 0
	global_load_dwordx4 v[136:139], v[140:141], off offset:16
	s_nop 0
	global_load_dwordx4 v[140:143], v[140:141], off
	ds_bpermute_b32 v204, v183, v203
	ds_bpermute_b32 v206, v183, v205
	s_and_saveexec_b64 s[2:3], vcc
	s_cbranch_execz .LBB0_686
	s_waitcnt vmcnt(3)
	v_mov_b32_e32 v128, 1.0
	s_waitcnt vmcnt(1)
	v_mov_b32_e32 v136, 0
	v_mov_b32_e32 v137, v136
	v_mov_b32_e32 v138, v136
	v_mov_b32_e32 v139, v136
	s_waitcnt vmcnt(0)
	v_mov_b32_e32 v140, v136
	v_mov_b32_e32 v141, v136
	v_mov_b32_e32 v142, v136
	v_mov_b32_e32 v143, v136
	v_mov_b32_e32 v129, v128
	v_mov_b32_e32 v130, v128
	v_mov_b32_e32 v131, v128
	v_mov_b32_e32 v132, v128
	v_mov_b32_e32 v133, v128
	v_mov_b32_e32 v134, v128
	v_mov_b32_e32 v135, v128
; __device__ __forceinline__ unsigned cvt_pk_bf16(float lo, float hi) { unsigned r; asm volatile("v_cvt_pk_bf16_f32 %0, %1, %2" : "=v"(r) : "v"(lo), "v"(hi)); return r; }
;     __device__ __forceinline__ void operator()(const f32x4 (&acc)[2][2][4][2], const Unit& u, int wr, int wc, int fr, int fq) const {
;     ...
;                 for (int m = 0; m < 4; ++m) {
;                     const int row = u.pm * BM + ai * HALF + wr * 64 + m * 16 + fr;
;                     const bool lat = row < MLAT; const int t = row & (SEQ - 1); const int pos = axis ? (t & 63) : (t >> 6);
;                     f32x4 c0 = *(const f32x4*)(ropec + pos * 16 + pb), c1 = *(const f32x4*)(ropec + pos * 16 + pb + 4), s0 = *(const f32x4*)(ropes + pos * 16 + pb), s1 = *(const f32x4*)(ropes + pos * 16 + pb + 4);
;                     if (!lat) { c0 = (f32x4){1.f, 1.f, 1.f, 1.f}; c1 = c0; s0 = (f32x4){0.f, 0.f, 0.f, 0.f}; s1 = s0; }
;                     if (!upper) { s0 = -s0; s1 = -s1; }
;                     bf16_t* rowp = dst + (size_t)row * DQK + u.pn * BM + wc * 32 + 8 * fq;
; #pragma unroll
;                     for (int bj = 0; bj < 2; ++bj) { const f32x4 a0 = acc[ai][bj][m][0], a1 = acc[ai][bj][m][1]; f32x4 p0, p1;
; #pragma unroll
;                         for (int i = 0; i < 4; ++i) {
;                             auto r0 = __builtin_amdgcn_permlane32_swap(__float_as_uint(a0[i]), __float_as_uint(a0[i]), false, false); p0[i] = __uint_as_float(upper ? r0[0] : r0[1]);
;                             auto r1 = __builtin_amdgcn_permlane32_swap(__float_as_uint(a1[i]), __float_as_uint(a1[i]), false, false); p1[i] = __uint_as_float(upper ? r1[0] : r1[1]); }
;                         const f32x4 o0 = (a0 * c0 + p0 * s0) * sc, o1 = (a1 * c1 + p1 * s1) * sc;
;                         { float ss = ((o0[0] * o0[0] + o0[1] * o0[1]) + (o0[2] * o0[2] + o0[3] * o0[3])) + ((o1[0] * o1[0] + o1[1] * o1[1]) + (o1[2] * o1[2] + o1[3] * o1[3]));
;                           ss += __shfl_xor(ss, 16); ss += __shfl_xor(ss, 32); gmax = fmaxf(gmax, ss); }
;                         u32x4 w; w.x = cvt_pk_bf16(o0[0], o0[1]); w.y = cvt_pk_bf16(o0[2], o0[3]); w.z = cvt_pk_bf16(o1[0], o1[1]); w.w = cvt_pk_bf16(o1[2], o1[3]);
;                         *(u32x4*)(rowp + bj * HALF) = w; }
.LBB0_686:
	s_or_b64 exec, exec, s[2:3]
	s_waitcnt vmcnt(1)
	v_cndmask_b32_e64 v228, v138, v139, s[0:1]
	v_cndmask_b32_e64 v238, v138, v139, s[0:1]
	s_waitcnt vmcnt(0)
	v_cndmask_b32_e64 v226, v140, v141, s[0:1]
	v_cndmask_b32_e64 v234, v140, v141, s[0:1]
	v_cndmask_b32_e64 v230, v136, v137, s[0:1]
	v_cndmask_b32_e64 v236, v136, v137, s[0:1]
	v_mov_b64_e32 v[136:137], s[8:9]
	v_mad_i64_i32 v[136:137], s[2:3], v180, s20, v[136:137]
	v_cndmask_b32_e64 v224, v142, v143, s[0:1]
	v_cndmask_b32_e64 v232, v142, v143, s[0:1]
	v_permlane32_swap_b32_e32 v54, v55
	v_cndmask_b32_e64 v240, v134, v135, s[0:1]
	v_pk_mul_f32 v[242:243], v[54:55], v[224:225] op_sel:[1,0] op_sel_hi:[0,0] neg_lo:[1,0]
	v_pk_fma_f32 v[216:217], v[54:55], v[240:241], v[242:243] op_sel_hi:[1,0,1]
	s_nop 1
	v_permlane32_swap_b32_e32 v216, v217
	v_permlane32_swap_b32_e32 v52, v53
	v_cndmask_b32_e64 v240, v132, v133, s[0:1]
	v_pk_mul_f32 v[242:243], v[52:53], v[226:227] op_sel:[1,0] op_sel_hi:[0,0] neg_lo:[1,0]
	v_pk_fma_f32 v[138:139], v[52:53], v[240:241], v[242:243] op_sel_hi:[1,0,1]
	s_nop 1
	v_permlane32_swap_b32_e32 v138, v139
	v_mov_b32_e32 v180, v178
	v_mov_b32_e32 v181, v178
	v_pk_mul_f32 v[216:217], v[180:181], v[216:217]
	v_pk_mul_f32 v[138:139], v[178:179], v[138:139]
	v_permlane32_swap_b32_e32 v50, v51
	v_cndmask_b32_e64 v240, v130, v131, s[0:1]
	v_pk_mul_f32 v[242:243], v[50:51], v[228:229] op_sel:[1,0] op_sel_hi:[0,0] neg_lo:[1,0]
	v_pk_fma_f32 v[208:209], v[50:51], v[240:241], v[242:243] op_sel_hi:[1,0,1]
	s_nop 1
	v_permlane32_swap_b32_e32 v208, v209
	v_lshl_add_u64 v[136:137], s[62:63], 1, v[136:137]
	v_permlane32_swap_b32_e32 v48, v49
	v_cndmask_b32_e64 v240, v128, v129, s[0:1]
	v_pk_mul_f32 v[242:243], v[48:49], v[230:231] op_sel:[1,0] op_sel_hi:[0,0] neg_lo:[1,0]
	v_pk_fma_f32 v[140:141], v[48:49], v[240:241], v[242:243] op_sel_hi:[1,0,1]
	s_nop 1
	v_permlane32_swap_b32_e32 v140, v141
	v_pk_mul_f32 v[218:219], v[180:181], v[208:209]
	v_mul_f32_e32 v207, v139, v139
	v_mul_f32_e32 v208, v217, v217
	v_lshl_add_u64 v[136:137], v[136:137], 0, s[28:29]
	v_pk_mul_f32 v[140:141], v[178:179], v[140:141]
	v_fmac_f32_e32 v207, v138, v138
	v_fmac_f32_e32 v208, v216, v216
	v_lshl_add_u64 v[136:137], v[136:137], 0, v[148:149]
	v_add_f32_e32 v207, v207, v208
	v_mul_f32_e32 v208, v141, v141
	v_cvt_pk_bf16_f32 v138, v138, v139
	v_cvt_pk_bf16_f32 v139, v216, v217
	v_fmac_f32_e32 v208, v140, v140
	v_cvt_pk_bf16_f32 v140, v140, v141
	v_cvt_pk_bf16_f32 v141, v218, v219
	global_store_dwordx4 v[136:137], v[138:141], off
	v_mul_f32_e32 v209, v219, v219
	v_fmac_f32_e32 v209, v218, v218
	v_add_f32_e32 v208, v208, v209
	v_permlane32_swap_b32_e32 v22, v23
	v_cndmask_b32_e64 v240, v134, v135, s[0:1]
	v_pk_mul_f32 v[242:243], v[22:23], v[232:233] op_sel:[1,0] op_sel_hi:[0,0] neg_lo:[1,0]
	v_pk_fma_f32 v[134:135], v[22:23], v[240:241], v[242:243] op_sel_hi:[1,0,1]
	s_nop 1
	v_permlane32_swap_b32_e32 v134, v135
	v_permlane32_swap_b32_e32 v20, v21
	v_cndmask_b32_e64 v240, v132, v133, s[0:1]
	v_pk_mul_f32 v[242:243], v[20:21], v[234:235] op_sel:[1,0] op_sel_hi:[0,0] neg_lo:[1,0]
	v_pk_fma_f32 v[132:133], v[20:21], v[240:241], v[242:243] op_sel_hi:[1,0,1]
	s_nop 1
	v_permlane32_swap_b32_e32 v132, v133
	v_pk_mul_f32 v[134:135], v[180:181], v[134:135]
	v_pk_mul_f32 v[132:133], v[178:179], v[132:133]
	v_permlane32_swap_b32_e32 v16, v17
	v_cndmask_b32_e64 v240, v128, v129, s[0:1]
	v_pk_mul_f32 v[242:243], v[16:17], v[236:237] op_sel:[1,0] op_sel_hi:[0,0] neg_lo:[1,0]
	v_pk_fma_f32 v[128:129], v[16:17], v[240:241], v[242:243] op_sel_hi:[1,0,1]
	s_nop 1
	v_permlane32_swap_b32_e32 v128, v129
	v_permlane32_swap_b32_e32 v18, v19
	v_cndmask_b32_e64 v240, v130, v131, s[0:1]
	v_pk_mul_f32 v[242:243], v[18:19], v[238:239] op_sel:[1,0] op_sel_hi:[0,0] neg_lo:[1,0]
	v_pk_fma_f32 v[130:131], v[18:19], v[240:241], v[242:243] op_sel_hi:[1,0,1]
	s_nop 1
	v_permlane32_swap_b32_e32 v130, v131
	v_or_b32_e32 v211, 32, v202
	v_pk_mul_f32 v[138:139], v[180:181], v[130:131]
	v_pk_mul_f32 v[130:131], v[178:179], v[128:129]
	v_mul_f32_e32 v128, v133, v133
	v_mul_f32_e32 v129, v135, v135
	v_fmac_f32_e32 v128, v132, v132
	v_fmac_f32_e32 v129, v134, v134
	v_add_f32_e32 v128, v128, v129
	v_mul_f32_e32 v129, v131, v131
	v_mul_f32_e32 v140, v139, v139
	v_fmac_f32_e32 v129, v130, v130
	v_fmac_f32_e32 v140, v138, v138
	v_add_f32_e32 v129, v129, v140
	v_add_f32_e32 v128, v128, v129
	ds_bpermute_b32 v129, v184, v128
	v_add_f32_e32 v207, v207, v208
	ds_bpermute_b32 v208, v184, v207
	v_cmp_lt_i32_e32 vcc, s97, v211
	s_waitcnt lgkmcnt(1)
	v_add_f32_e32 v209, v128, v129
	v_cvt_pk_bf16_f32 v128, v132, v133
	v_cvt_pk_bf16_f32 v129, v134, v135
	v_cvt_pk_bf16_f32 v130, v130, v131
	v_cvt_pk_bf16_f32 v131, v138, v139
	global_store_dwordx4 v[136:137], v[128:131], off offset:256
	v_mov_b32_e32 v137, v149
	s_waitcnt lgkmcnt(0)
	v_add_f32_e32 v207, v207, v208
	v_mov_b32_e32 v128, s44
	v_cndmask_b32_e64 v128, v211, v128, s[10:11]
	v_lshlrev_b32_e32 v128, 6, v128
	v_and_b32_e32 v136, 0xfc0, v128
	v_lshl_add_u64 v[132:133], v[168:169], 0, v[136:137]
	v_lshl_add_u64 v[140:141], v[170:171], 0, v[136:137]
	global_load_dwordx4 v[128:131], v[132:133], off offset:16
	s_nop 0
	global_load_dwordx4 v[132:135], v[132:133], off
	s_nop 0
	global_load_dwordx4 v[136:139], v[140:141], off offset:16
	s_nop 0
	global_load_dwordx4 v[140:143], v[140:141], off
	ds_bpermute_b32 v208, v183, v207
	ds_bpermute_b32 v210, v183, v209
	s_and_saveexec_b64 s[2:3], vcc
	s_cbranch_execz .LBB0_688
	s_waitcnt vmcnt(3)
	v_mov_b32_e32 v128, 1.0
	s_waitcnt vmcnt(1)
	v_mov_b32_e32 v136, 0
	v_mov_b32_e32 v137, v136
	v_mov_b32_e32 v138, v136
	v_mov_b32_e32 v139, v136
	s_waitcnt vmcnt(0)
	v_mov_b32_e32 v140, v136
	v_mov_b32_e32 v141, v136
	v_mov_b32_e32 v142, v136
	v_mov_b32_e32 v143, v136
	v_mov_b32_e32 v129, v128
	v_mov_b32_e32 v130, v128
	v_mov_b32_e32 v131, v128
	v_mov_b32_e32 v132, v128
	v_mov_b32_e32 v133, v128
	v_mov_b32_e32 v134, v128
	v_mov_b32_e32 v135, v128
; __device__ __forceinline__ unsigned cvt_pk_bf16(float lo, float hi) { unsigned r; asm volatile("v_cvt_pk_bf16_f32 %0, %1, %2" : "=v"(r) : "v"(lo), "v"(hi)); return r; }
;     __device__ __forceinline__ void operator()(const f32x4 (&acc)[2][2][4][2], const Unit& u, int wr, int wc, int fr, int fq) const {
;     ...
;                 for (int m = 0; m < 4; ++m) {
;                     const int row = u.pm * BM + ai * HALF + wr * 64 + m * 16 + fr;
;                     const bool lat = row < MLAT; const int t = row & (SEQ - 1); const int pos = axis ? (t & 63) : (t >> 6);
;                     f32x4 c0 = *(const f32x4*)(ropec + pos * 16 + pb), c1 = *(const f32x4*)(ropec + pos * 16 + pb + 4), s0 = *(const f32x4*)(ropes + pos * 16 + pb), s1 = *(const f32x4*)(ropes + pos * 16 + pb + 4);
;                     if (!lat) { c0 = (f32x4){1.f, 1.f, 1.f, 1.f}; c1 = c0; s0 = (f32x4){0.f, 0.f, 0.f, 0.f}; s1 = s0; }
;                     if (!upper) { s0 = -s0; s1 = -s1; }
;                     bf16_t* rowp = dst + (size_t)row * DQK + u.pn * BM + wc * 32 + 8 * fq;
; #pragma unroll
;                     for (int bj = 0; bj < 2; ++bj) { const f32x4 a0 = acc[ai][bj][m][0], a1 = acc[ai][bj][m][1]; f32x4 p0, p1;
; #pragma unroll
;                         for (int i = 0; i < 4; ++i) {
;                             auto r0 = __builtin_amdgcn_permlane32_swap(__float_as_uint(a0[i]), __float_as_uint(a0[i]), false, false); p0[i] = __uint_as_float(upper ? r0[0] : r0[1]);
;                             auto r1 = __builtin_amdgcn_permlane32_swap(__float_as_uint(a1[i]), __float_as_uint(a1[i]), false, false); p1[i] = __uint_as_float(upper ? r1[0] : r1[1]); }
;                         const f32x4 o0 = (a0 * c0 + p0 * s0) * sc, o1 = (a1 * c1 + p1 * s1) * sc;
;                         { float ss = ((o0[0] * o0[0] + o0[1] * o0[1]) + (o0[2] * o0[2] + o0[3] * o0[3])) + ((o1[0] * o1[0] + o1[1] * o1[1]) + (o1[2] * o1[2] + o1[3] * o1[3]));
;                           ss += __shfl_xor(ss, 16); ss += __shfl_xor(ss, 32); gmax = fmaxf(gmax, ss); }
;                         u32x4 w; w.x = cvt_pk_bf16(o0[0], o0[1]); w.y = cvt_pk_bf16(o0[2], o0[3]); w.z = cvt_pk_bf16(o1[0], o1[1]); w.w = cvt_pk_bf16(o1[2], o1[3]);
;                         *(u32x4*)(rowp + bj * HALF) = w; }
.LBB0_688:
	s_or_b64 exec, exec, s[2:3]
	s_waitcnt vmcnt(1)
	v_cndmask_b32_e64 v228, v138, v139, s[0:1]
	v_cndmask_b32_e64 v238, v138, v139, s[0:1]
	s_waitcnt vmcnt(0)
	v_cndmask_b32_e64 v226, v140, v141, s[0:1]
	v_cndmask_b32_e64 v234, v140, v141, s[0:1]
	v_cndmask_b32_e64 v230, v136, v137, s[0:1]
	v_cndmask_b32_e64 v236, v136, v137, s[0:1]
	v_mov_b64_e32 v[136:137], s[8:9]
	v_mad_i64_i32 v[136:137], s[2:3], v211, s20, v[136:137]
	v_cndmask_b32_e64 v224, v142, v143, s[0:1]
	v_cndmask_b32_e64 v232, v142, v143, s[0:1]
	v_permlane32_swap_b32_e32 v46, v47
	v_cndmask_b32_e64 v240, v134, v135, s[0:1]
	v_pk_mul_f32 v[242:243], v[46:47], v[224:225] op_sel:[1,0] op_sel_hi:[0,0] neg_lo:[1,0]
	v_pk_fma_f32 v[212:213], v[46:47], v[240:241], v[242:243] op_sel_hi:[1,0,1]
	s_nop 1
	v_permlane32_swap_b32_e32 v212, v213
	v_permlane32_swap_b32_e32 v44, v45
	v_cndmask_b32_e64 v240, v132, v133, s[0:1]
	v_pk_mul_f32 v[242:243], v[44:45], v[226:227] op_sel:[1,0] op_sel_hi:[0,0] neg_lo:[1,0]
	v_pk_fma_f32 v[138:139], v[44:45], v[240:241], v[242:243] op_sel_hi:[1,0,1]
	s_nop 1
	v_permlane32_swap_b32_e32 v138, v139
	v_pk_mul_f32 v[222:223], v[180:181], v[212:213]
	v_pk_mul_f32 v[138:139], v[178:179], v[138:139]
	v_permlane32_swap_b32_e32 v42, v43
	v_cndmask_b32_e64 v240, v130, v131, s[0:1]
	v_pk_mul_f32 v[242:243], v[42:43], v[228:229] op_sel:[1,0] op_sel_hi:[0,0] neg_lo:[1,0]
	v_pk_fma_f32 v[212:213], v[42:43], v[240:241], v[242:243] op_sel_hi:[1,0,1]
	s_nop 1
	v_permlane32_swap_b32_e32 v212, v213
	v_lshl_add_u64 v[136:137], s[62:63], 1, v[136:137]
	v_permlane32_swap_b32_e32 v40, v41
	v_cndmask_b32_e64 v240, v128, v129, s[0:1]
	v_pk_mul_f32 v[242:243], v[40:41], v[230:231] op_sel:[1,0] op_sel_hi:[0,0] neg_lo:[1,0]
	v_pk_fma_f32 v[140:141], v[40:41], v[240:241], v[242:243] op_sel_hi:[1,0,1]
	s_nop 1
	v_permlane32_swap_b32_e32 v140, v141
	v_pk_mul_f32 v[220:221], v[180:181], v[212:213]
	v_mul_f32_e32 v211, v139, v139
	v_mul_f32_e32 v212, v223, v223
	v_lshl_add_u64 v[136:137], v[136:137], 0, s[28:29]
	v_pk_mul_f32 v[140:141], v[178:179], v[140:141]
	v_fmac_f32_e32 v211, v138, v138
	v_fmac_f32_e32 v212, v222, v222
	v_lshl_add_u64 v[136:137], v[136:137], 0, v[148:149]
	v_add_f32_e32 v211, v211, v212
	v_mul_f32_e32 v212, v141, v141
	v_cvt_pk_bf16_f32 v138, v138, v139
	v_cvt_pk_bf16_f32 v139, v222, v223
	v_fmac_f32_e32 v212, v140, v140
	v_cvt_pk_bf16_f32 v140, v140, v141
	v_cvt_pk_bf16_f32 v141, v220, v221
	global_store_dwordx4 v[136:137], v[138:141], off
	v_mul_f32_e32 v213, v221, v221
	v_fmac_f32_e32 v213, v220, v220
	v_add_f32_e32 v212, v212, v213
	v_permlane32_swap_b32_e32 v14, v15
	v_cndmask_b32_e64 v240, v134, v135, s[0:1]
	v_pk_mul_f32 v[242:243], v[14:15], v[232:233] op_sel:[1,0] op_sel_hi:[0,0] neg_lo:[1,0]
	v_pk_fma_f32 v[134:135], v[14:15], v[240:241], v[242:243] op_sel_hi:[1,0,1]
	s_nop 1
	v_permlane32_swap_b32_e32 v134, v135
	v_permlane32_swap_b32_e32 v12, v13
	v_cndmask_b32_e64 v240, v132, v133, s[0:1]
	v_pk_mul_f32 v[242:243], v[12:13], v[234:235] op_sel:[1,0] op_sel_hi:[0,0] neg_lo:[1,0]
	v_pk_fma_f32 v[132:133], v[12:13], v[240:241], v[242:243] op_sel_hi:[1,0,1]
	s_nop 1
	v_permlane32_swap_b32_e32 v132, v133
	v_pk_mul_f32 v[134:135], v[180:181], v[134:135]
	v_pk_mul_f32 v[132:133], v[178:179], v[132:133]
	v_permlane32_swap_b32_e32 v8, v9
	v_cndmask_b32_e64 v240, v128, v129, s[0:1]
	v_pk_mul_f32 v[242:243], v[8:9], v[236:237] op_sel:[1,0] op_sel_hi:[0,0] neg_lo:[1,0]
	v_pk_fma_f32 v[128:129], v[8:9], v[240:241], v[242:243] op_sel_hi:[1,0,1]
	s_nop 1
	v_permlane32_swap_b32_e32 v128, v129
	v_permlane32_swap_b32_e32 v10, v11
	v_cndmask_b32_e64 v240, v130, v131, s[0:1]
	v_pk_mul_f32 v[242:243], v[10:11], v[238:239] op_sel:[1,0] op_sel_hi:[0,0] neg_lo:[1,0]
	v_pk_fma_f32 v[130:131], v[10:11], v[240:241], v[242:243] op_sel_hi:[1,0,1]
	s_nop 1
	v_permlane32_swap_b32_e32 v130, v131
	v_or_b32_e32 v202, 48, v202
	v_pk_mul_f32 v[138:139], v[180:181], v[130:131]
	v_pk_mul_f32 v[130:131], v[178:179], v[128:129]
	v_mul_f32_e32 v128, v133, v133
	v_mul_f32_e32 v129, v135, v135
	v_fmac_f32_e32 v128, v132, v132
	v_fmac_f32_e32 v129, v134, v134
	v_add_f32_e32 v128, v128, v129
	v_mul_f32_e32 v129, v131, v131
	v_mul_f32_e32 v140, v139, v139
	v_fmac_f32_e32 v129, v130, v130
	v_fmac_f32_e32 v140, v138, v138
	v_add_f32_e32 v129, v129, v140
	v_add_f32_e32 v128, v128, v129
	ds_bpermute_b32 v129, v184, v128
	v_add_f32_e32 v211, v211, v212
	ds_bpermute_b32 v212, v184, v211
	v_cmp_lt_i32_e32 vcc, s97, v202
	s_waitcnt lgkmcnt(1)
	v_add_f32_e32 v180, v128, v129
	v_cvt_pk_bf16_f32 v128, v132, v133
	v_cvt_pk_bf16_f32 v129, v134, v135
	v_cvt_pk_bf16_f32 v130, v130, v131
	v_cvt_pk_bf16_f32 v131, v138, v139
	global_store_dwordx4 v[136:137], v[128:131], off offset:256
	v_mov_b32_e32 v137, v149
	s_waitcnt lgkmcnt(0)
	v_add_f32_e32 v211, v211, v212
	v_mov_b32_e32 v128, s44
	v_cndmask_b32_e64 v128, v202, v128, s[10:11]
	v_lshlrev_b32_e32 v128, 6, v128
	v_and_b32_e32 v136, 0xfc0, v128
	v_lshl_add_u64 v[132:133], v[168:169], 0, v[136:137]
	v_lshl_add_u64 v[140:141], v[170:171], 0, v[136:137]
	global_load_dwordx4 v[128:131], v[132:133], off offset:16
	s_nop 0
	global_load_dwordx4 v[132:135], v[132:133], off
	s_nop 0
	global_load_dwordx4 v[136:139], v[140:141], off offset:16
	s_nop 0
	global_load_dwordx4 v[140:143], v[140:141], off
	ds_bpermute_b32 v212, v183, v211
	ds_bpermute_b32 v181, v183, v180
	s_and_saveexec_b64 s[2:3], vcc
	s_cbranch_execz .LBB0_690
	s_waitcnt vmcnt(3)
	v_mov_b32_e32 v128, 1.0
	s_waitcnt vmcnt(1)
	v_mov_b32_e32 v136, 0
	v_mov_b32_e32 v137, v136
	v_mov_b32_e32 v138, v136
	v_mov_b32_e32 v139, v136
	s_waitcnt vmcnt(0)
	v_mov_b32_e32 v140, v136
	v_mov_b32_e32 v141, v136
	v_mov_b32_e32 v142, v136
	v_mov_b32_e32 v143, v136
	v_mov_b32_e32 v129, v128
	v_mov_b32_e32 v130, v128
	v_mov_b32_e32 v131, v128
	v_mov_b32_e32 v132, v128
	v_mov_b32_e32 v133, v128
	v_mov_b32_e32 v134, v128
	v_mov_b32_e32 v135, v128
;     __device__ __forceinline__ void operator()(const f32x4 (&acc)[2][2][4][2], const Unit& u, int wr, int wc, int fr, int fq) const {
;     ...
;             const int axis = wc & 1, pb = 8 * (fq & 1); const bool upper = fq >= 2; float gmax = 0.f;
; #pragma unroll
;             for (int ai = 0; ai < 2; ++ai)
; #pragma unroll
;                 for (int m = 0; m < 4; ++m) {
;                     const int row = u.pm * BM + ai * HALF + wr * 64 + m * 16 + fr;
;                     const bool lat = row < MLAT; const int t = row & (SEQ - 1); const int pos = axis ? (t & 63) : (t >> 6);
;                     f32x4 c0 = *(const f32x4*)(ropec + pos * 16 + pb), c1 = *(const f32x4*)(ropec + pos * 16 + pb + 4), s0 = *(const f32x4*)(ropes + pos * 16 + pb), s1 = *(const f32x4*)(ropes + pos * 16 + pb + 4);
;                     if (!lat) { c0 = (f32x4){1.f, 1.f, 1.f, 1.f}; c1 = c0; s0 = (f32x4){0.f, 0.f, 0.f, 0.f}; s1 = s0; }
;                     if (!upper) { s0 = -s0; s1 = -s1; }
;                     bf16_t* rowp = dst + (size_t)row * DQK + u.pn * BM + wc * 32 + 8 * fq;
; #pragma unroll
;                     for (int bj = 0; bj < 2; ++bj) { const f32x4 a0 = acc[ai][bj][m][0], a1 = acc[ai][bj][m][1]; f32x4 p0, p1;
; #pragma unroll
;                         for (int i = 0; i < 4; ++i) {
;                             auto r0 = __builtin_amdgcn_permlane32_swap(__float_as_uint(a0[i]), __float_as_uint(a0[i]), false, false); p0[i] = __uint_as_float(upper ? r0[0] : r0[1]);
;                             auto r1 = __builtin_amdgcn_permlane32_swap(__float_as_uint(a1[i]), __float_as_uint(a1[i]), false, false); p1[i] = __uint_as_float(upper ? r1[0] : r1[1]); }
;                         const f32x4 o0 = (a0 * c0 + p0 * s0) * sc, o1 = (a1 * c1 + p1 * s1) * sc;
;                         { float ss = ((o0[0] * o0[0] + o0[1] * o0[1]) + (o0[2] * o0[2] + o0[3] * o0[3])) + ((o1[0] * o1[0] + o1[1] * o1[1]) + (o1[2] * o1[2] + o1[3] * o1[3]));
;                           ss += __shfl_xor(ss, 16); ss += __shfl_xor(ss, 32); gmax = fmaxf(gmax, ss); }
;                         u32x4 w; w.x = cvt_pk_bf16(o0[0], o0[1]); w.y = cvt_pk_bf16(o0[2], o0[3]); w.z = cvt_pk_bf16(o1[0], o1[1]); w.w = cvt_pk_bf16(o1[2], o1[3]);
;                         *(u32x4*)(rowp + bj * HALF) = w; }
;                 }
; #pragma unroll
;             for (int o = 1; o < 16; o <<= 1) gmax = fmaxf(gmax, __shfl_xor(gmax, o));
.LBB0_690:
	s_or_b64 exec, exec, s[2:3]
	v_add_f32_e32 v185, v185, v186
	v_add_f32_e32 v186, v187, v188
	v_max3_f32 v185, v185, 0, v186
	v_add_f32_e32 v186, v189, v190
	v_add_f32_e32 v187, v191, v192
	v_max3_f32 v185, v185, v186, v187
	v_add_f32_e32 v186, v193, v194
	v_add_f32_e32 v187, v195, v196
	v_max3_f32 v185, v185, v186, v187
	v_add_f32_e32 v186, v197, v198
	v_add_f32_e32 v187, v199, v201
	v_max3_f32 v185, v185, v186, v187
	v_add_f32_e32 v186, v203, v204
	v_add_f32_e32 v187, v205, v206
	v_max3_f32 v185, v185, v186, v187
	v_add_f32_e32 v186, v207, v208
	v_add_f32_e32 v187, v209, v210
	v_max3_f32 v185, v185, v186, v187
	s_waitcnt lgkmcnt(1)
	v_add_f32_e32 v186, v211, v212
	s_waitcnt lgkmcnt(0)
	v_add_f32_e32 v180, v180, v181
	v_max3_f32 v185, v185, v186, v180
	s_waitcnt vmcnt(1)
	v_cndmask_b32_e64 v228, v138, v139, s[0:1]
	v_cndmask_b32_e64 v238, v138, v139, s[0:1]
	s_waitcnt vmcnt(0)
	v_cndmask_b32_e64 v230, v136, v137, s[0:1]
	v_cndmask_b32_e64 v236, v136, v137, s[0:1]
	v_cndmask_b32_e64 v224, v140, v141, s[0:1]
	v_cndmask_b32_e64 v234, v140, v141, s[0:1]
	v_mov_b64_e32 v[136:137], s[8:9]
	v_mad_i64_i32 v[136:137], s[2:3], v202, s20, v[136:137]
	v_lshl_add_u64 v[136:137], s[62:63], 1, v[136:137]
	v_lshl_add_u64 v[136:137], v[136:137], 0, s[28:29]
	v_lshl_add_u64 v[136:137], v[136:137], 0, v[148:149]
	v_cndmask_b32_e64 v226, v142, v143, s[0:1]
	v_cndmask_b32_e64 v232, v142, v143, s[0:1]
	v_permlane32_swap_b32_e32 v36, v37
	v_cndmask_b32_e64 v240, v132, v133, s[0:1]
	v_pk_mul_f32 v[242:243], v[36:37], v[224:225] op_sel:[1,0] op_sel_hi:[0,0] neg_lo:[1,0]
	v_pk_fma_f32 v[138:139], v[36:37], v[240:241], v[242:243] op_sel_hi:[1,0,1]
	s_nop 1
	v_permlane32_swap_b32_e32 v138, v139
	v_permlane32_swap_b32_e32 v38, v39
	v_cndmask_b32_e64 v240, v134, v135, s[0:1]
	v_pk_mul_f32 v[242:243], v[38:39], v[226:227] op_sel:[1,0] op_sel_hi:[0,0] neg_lo:[1,0]
	v_pk_fma_f32 v[190:191], v[38:39], v[240:241], v[242:243] op_sel_hi:[1,0,1]
	s_nop 1
	v_permlane32_swap_b32_e32 v190, v191
	v_mov_b32_e32 v194, v178
	v_mov_b32_e32 v195, v178
	v_pk_mul_f32 v[190:191], v[194:195], v[190:191]
	v_pk_mul_f32 v[138:139], v[178:179], v[138:139]
	v_permlane32_swap_b32_e32 v34, v35
	v_cndmask_b32_e64 v240, v130, v131, s[0:1]
	v_pk_mul_f32 v[242:243], v[34:35], v[228:229] op_sel:[1,0] op_sel_hi:[0,0] neg_lo:[1,0]
	v_pk_fma_f32 v[192:193], v[34:35], v[240:241], v[242:243] op_sel_hi:[1,0,1]
	s_nop 1
	v_permlane32_swap_b32_e32 v192, v193
	v_permlane32_swap_b32_e32 v32, v33
	v_cndmask_b32_e64 v240, v128, v129, s[0:1]
	v_pk_mul_f32 v[242:243], v[32:33], v[230:231] op_sel:[1,0] op_sel_hi:[0,0] neg_lo:[1,0]
	v_pk_fma_f32 v[140:141], v[32:33], v[240:241], v[242:243] op_sel_hi:[1,0,1]
	s_nop 1
	v_permlane32_swap_b32_e32 v140, v141
	v_mul_f32_e32 v148, v139, v139
	v_mul_f32_e32 v196, v191, v191
	v_pk_mul_f32 v[192:193], v[194:195], v[192:193]
	v_pk_mul_f32 v[140:141], v[178:179], v[140:141]
	v_fmac_f32_e32 v148, v138, v138
	v_fmac_f32_e32 v196, v190, v190
	v_add_f32_e32 v148, v148, v196
	v_mul_f32_e32 v196, v141, v141
	v_mul_f32_e32 v197, v193, v193
	v_cvt_pk_bf16_f32 v138, v138, v139
	v_cvt_pk_bf16_f32 v139, v190, v191
	v_fmac_f32_e32 v196, v140, v140
	v_fmac_f32_e32 v197, v192, v192
	v_cvt_pk_bf16_f32 v140, v140, v141
	v_cvt_pk_bf16_f32 v141, v192, v193
	global_store_dwordx4 v[136:137], v[138:141], off
	v_add_f32_e32 v196, v196, v197
	v_add_f32_e32 v148, v148, v196
	ds_bpermute_b32 v196, v184, v148
	s_waitcnt lgkmcnt(0)
	v_add_f32_e32 v148, v148, v196
	ds_bpermute_b32 v196, v183, v148
	s_waitcnt lgkmcnt(0)
	v_add_f32_e32 v148, v148, v196
	v_permlane32_swap_b32_e32 v6, v7
	v_cndmask_b32_e64 v240, v134, v135, s[0:1]
	v_pk_mul_f32 v[242:243], v[6:7], v[232:233] op_sel:[1,0] op_sel_hi:[0,0] neg_lo:[1,0]
	v_pk_fma_f32 v[134:135], v[6:7], v[240:241], v[242:243] op_sel_hi:[1,0,1]
	s_nop 1
	v_permlane32_swap_b32_e32 v134, v135
	v_permlane32_swap_b32_e32 v4, v5
	v_cndmask_b32_e64 v240, v132, v133, s[0:1]
	v_pk_mul_f32 v[242:243], v[4:5], v[234:235] op_sel:[1,0] op_sel_hi:[0,0] neg_lo:[1,0]
	v_pk_fma_f32 v[132:133], v[4:5], v[240:241], v[242:243] op_sel_hi:[1,0,1]
	s_nop 1
	v_permlane32_swap_b32_e32 v132, v133
	v_pk_mul_f32 v[134:135], v[194:195], v[134:135]
	v_pk_mul_f32 v[132:133], v[178:179], v[132:133]
	v_permlane32_swap_b32_e32 v0, v1
	v_cndmask_b32_e64 v240, v128, v129, s[0:1]
	v_pk_mul_f32 v[242:243], v[0:1], v[236:237] op_sel:[1,0] op_sel_hi:[0,0] neg_lo:[1,0]
	v_pk_fma_f32 v[128:129], v[0:1], v[240:241], v[242:243] op_sel_hi:[1,0,1]
	s_nop 1
	v_permlane32_swap_b32_e32 v128, v129
	v_permlane32_swap_b32_e32 v2, v3
	v_cndmask_b32_e64 v240, v130, v131, s[0:1]
	v_pk_mul_f32 v[242:243], v[2:3], v[238:239] op_sel:[1,0] op_sel_hi:[0,0] neg_lo:[1,0]
	v_pk_fma_f32 v[130:131], v[2:3], v[240:241], v[242:243] op_sel_hi:[1,0,1]
	s_nop 1
	v_permlane32_swap_b32_e32 v130, v131
	s_nop 0
	v_pk_mul_f32 v[138:139], v[194:195], v[130:131]
	v_pk_mul_f32 v[130:131], v[178:179], v[128:129]
	v_mul_f32_e32 v128, v133, v133
	v_mul_f32_e32 v129, v135, v135
	v_fmac_f32_e32 v128, v132, v132
	v_fmac_f32_e32 v129, v134, v134
	v_add_f32_e32 v128, v128, v129
	v_mul_f32_e32 v129, v131, v131
	v_mul_f32_e32 v140, v139, v139
	v_fmac_f32_e32 v129, v130, v130
	v_fmac_f32_e32 v140, v138, v138
	v_add_f32_e32 v129, v129, v140
	v_add_f32_e32 v128, v128, v129
	ds_bpermute_b32 v129, v184, v128
	s_waitcnt lgkmcnt(0)
	v_add_f32_e32 v128, v128, v129
	ds_bpermute_b32 v129, v183, v128
	s_waitcnt lgkmcnt(0)
	v_add_f32_e32 v128, v128, v129
	v_max3_f32 v140, v185, v148, v128
	v_cvt_pk_bf16_f32 v128, v132, v133
	v_cvt_pk_bf16_f32 v129, v134, v135
	v_cvt_pk_bf16_f32 v130, v130, v131
	v_cvt_pk_bf16_f32 v131, v138, v139
	global_store_dwordx4 v[136:137], v[128:131], off offset:256
	s_nop 1
	v_xor_b32_e32 v128, 1, v167
	v_cmp_lt_i32_e32 vcc, v128, v182
	v_xor_b32_e32 v129, 2, v167
	s_nop 0
	v_cndmask_b32_e32 v128, v167, v128, vcc
	v_lshlrev_b32_e32 v128, 2, v128
	ds_bpermute_b32 v128, v128, v140
	v_cmp_lt_i32_e32 vcc, v129, v182
	s_waitcnt lgkmcnt(0)
	v_max_f32_e32 v128, v128, v128
	v_cndmask_b32_e32 v129, v167, v129, vcc
	v_max_f32_e32 v128, v140, v128
	v_lshlrev_b32_e32 v129, 2, v129
	ds_bpermute_b32 v129, v129, v128
	s_waitcnt lgkmcnt(0)
	v_max_f32_e32 v129, v129, v129
	v_max_f32_e32 v128, v128, v129
	v_xor_b32_e32 v129, 4, v167
	v_cmp_lt_i32_e32 vcc, v129, v182
	s_nop 1
	v_cndmask_b32_e32 v129, v167, v129, vcc
	v_lshlrev_b32_e32 v129, 2, v129
	ds_bpermute_b32 v129, v129, v128
	s_waitcnt lgkmcnt(0)
	v_max_f32_e32 v129, v129, v129
	v_max_f32_e32 v128, v128, v129
	v_xor_b32_e32 v129, 8, v167
	v_cmp_lt_i32_e32 vcc, v129, v182
	s_nop 1
	v_cndmask_b32_e32 v129, v167, v129, vcc
	v_lshlrev_b32_e32 v129, 2, v129
	ds_bpermute_b32 v129, v129, v128
	s_and_saveexec_b64 s[2:3], s[4:5]
	s_cbranch_execz .LBB0_695
	s_waitcnt lgkmcnt(0)
	v_max_f32_e32 v129, v129, v129
	v_max_f32_e32 v128, v128, v128
	s_mov_b64 s[8:9], exec
	v_max_f32_e32 v128, v128, v129
	s_mov_b32 s28, 0
